# v13 + gate epilogue n=1 load group issued with n=0 group + G3 epilogue bias vectors loaded once per tile (was 16 conditional load+wait round trips)
# speedup vs baseline: 1.0142x; 1.0142x over previous
.LBB0_318:
	s_lshl_b32 s6, s67, 7
	v_mov_b32_e32 v104, v191
	v_mov_b32_e32 v108, v190
	s_and_b32 s6, s6, 0x80
	s_ashr_i32 s7, s67, 1
	s_or_b32 s6, s6, s56
	v_lshl_add_u32 v104, v104, 2, s6
	s_lshl_b32 s6, s36, 8
	s_lshl_b32 s38, s7, 9
	s_add_i32 s27, s6, s55
	s_lshl_b32 s6, s7, 8
	s_ashr_i32 s39, s38, 31
	s_ashr_i32 s7, s6, 31
	s_lshl_b64 s[38:39], s[38:39], 2
	v_ashrrev_i32_e32 v105, 31, v104
	s_add_u32 s38, s10, s38
	v_lshlrev_b64 v[106:107], 2, v[104:105]
	v_add_lshl_u32 v105, s27, v108, 11
	s_addc_u32 s39, s11, s39
	v_add3_u32 v148, v105, s6, v104
	v_lshl_add_u64 v[154:155], v[148:149], 1, s[12:13]
	v_lshl_add_u64 v[156:157], s[38:39], 0, v[106:107]
	global_load_dwordx2 v[196:197], v[154:155], off
	global_load_dwordx4 v[112:115], v[156:157], off
	global_load_dwordx4 v[108:111], v[156:157], off offset:1024
	s_lshl_b64 s[6:7], s[6:7], 2
	s_add_u32 s6, s14, s6
	s_addc_u32 s7, s15, s7
	v_lshl_add_u64 v[158:159], s[6:7], 0, v[106:107]
	global_load_dwordx4 v[104:107], v[158:159], off
	s_mov_b32 s6, 0x10000
	v_add_co_u32_e32 v160, vcc, s6, v154
	s_mov_b32 s7, 0x20000
	s_nop 0
	v_addc_co_u32_e32 v161, vcc, 0, v155, vcc
	v_add_co_u32_e32 v162, vcc, s7, v154
	s_mov_b32 s27, 0x30000
	s_nop 0
	v_addc_co_u32_e32 v163, vcc, 0, v155, vcc
	v_add_co_u32_e32 v164, vcc, s27, v154
	s_mov_b32 s29, 0x80000
	s_nop 0
	v_addc_co_u32_e32 v165, vcc, 0, v155, vcc
	v_add_co_u32_e32 v166, vcc, s29, v154
	s_mov_b32 s36, 0x90000
	s_nop 0
	v_addc_co_u32_e32 v167, vcc, 0, v155, vcc
	v_add_co_u32_e32 v168, vcc, s36, v154
	s_mov_b32 s38, 0xa0000
	s_nop 0
	v_addc_co_u32_e32 v169, vcc, 0, v155, vcc
	v_add_co_u32_e32 v170, vcc, s38, v154
	s_mov_b32 s39, 0xb0000
	s_nop 0
	v_addc_co_u32_e32 v171, vcc, 0, v155, vcc
	v_add_co_u32_e32 v172, vcc, s39, v154
	s_mov_b64 s[72:73], s[58:59]
	s_nop 0
	v_addc_co_u32_e32 v173, vcc, 0, v155, vcc
	global_load_dwordx2 v[188:189], v[160:161], off
	global_load_dwordx2 v[186:187], v[162:163], off
	global_load_dwordx2 v[182:183], v[164:165], off
	global_load_dwordx2 v[180:181], v[166:167], off
	global_load_dwordx2 v[178:179], v[168:169], off
	global_load_dwordx2 v[176:177], v[170:171], off
	global_load_dwordx2 v[174:175], v[172:173], off
	v_readlane_b32 s68, v254, 23
	v_readlane_b32 s69, v254, 24
	global_load_dwordx4 v[228:231], v[156:157], off offset:1088
	global_load_dwordx4 v[232:235], v[156:157], off offset:64
	global_load_dwordx2 v[250:251], v[154:155], off offset:32
	global_load_dwordx4 v[224:227], v[158:159], off offset:64
	global_load_dwordx2 v[248:249], v[160:161], off offset:32
	global_load_dwordx2 v[246:247], v[162:163], off offset:32
	global_load_dwordx2 v[244:245], v[164:165], off offset:32
	global_load_dwordx2 v[242:243], v[166:167], off offset:32
	global_load_dwordx2 v[240:241], v[168:169], off offset:32
	global_load_dwordx2 v[238:239], v[170:171], off offset:32
	global_load_dwordx2 v[236:237], v[172:173], off offset:32
	s_waitcnt vmcnt(11)
	v_add_f32_e32 v136, v136, v112
	v_add_f32_e32 v137, v137, v113
	v_add_f32_e32 v132, v132, v108
	v_mul_f32_e32 v136, 0xbfb8aa3b, v136
	v_mul_f32_e32 v137, 0xbfb8aa3b, v137
	v_mul_f32_e32 v132, 0xbfb8aa3b, v132
	v_exp_f32_e32 v136, v136
	v_exp_f32_e32 v137, v137
	v_exp_f32_e32 v132, v132
	v_add_f32_e32 v133, v133, v109
	v_mul_f32_e32 v133, 0xbfb8aa3b, v133
	v_exp_f32_e32 v199, v133
	v_add_f32_e32 v133, 1.0, v136
	v_add_f32_e32 v137, 1.0, v137
	v_add_f32_e32 v136, 1.0, v132
	v_rcp_f32_e32 v132, v133
	v_rcp_f32_e32 v133, v137
	v_rcp_f32_e32 v136, v136
	v_lshlrev_b32_e32 v198, 16, v196
	v_add_f32_e32 v137, 1.0, v199
	v_pk_mul_f32 v[132:133], v[132:133], s[22:23] op_sel_hi:[1,0]
	v_rcp_f32_e32 v199, v137
	v_pk_mul_f32 v[132:133], v[104:105], v[132:133]
	v_mul_f32_e32 v198, v136, v198
	v_pk_add_f32 v[136:137], v[132:133], v[132:133]
	v_and_b32_e32 v196, 0xffff0000, v196
	v_fma_f32 v200, v136, s66, 1.0
	v_mul_f32_e32 v201, 0x3e4ccccd, v136
	v_mul_f32_e32 v205, 0x3fb8aa3b, v136
	v_mul_f32_e32 v202, 0x3e800000, v136
	v_fma_f32 v200, v201, v200, 1.0
	v_exp_f32_e32 v201, v205
	v_mul_f32_e32 v203, 0x3eaaaaab, v136
	v_fma_f32 v200, v202, v200, 1.0
	v_mul_f32_e32 v204, 0.5, v136
	v_fma_f32 v200, v203, v200, 1.0
	v_fma_f32 v200, v204, v200, 1.0
	v_mul_f32_e64 v200, v200, -v136
	v_sub_f32_e32 v201, 1.0, v201
	v_cmp_lt_f32_e32 vcc, -0.5, v136
	v_fma_f32 v206, v137, s66, 1.0
	v_mul_f32_e32 v202, 0.5, v137
	v_cndmask_b32_e32 v136, v201, v200, vcc
	v_mul_f32_e32 v200, 0x3e4ccccd, v137
	v_fma_f32 v200, v200, v206, 1.0
	v_mul_f32_e32 v201, 0x3e800000, v137
	v_fma_f32 v200, v201, v200, 1.0
	v_mul_f32_e32 v201, 0x3eaaaaab, v137
	v_fma_f32 v200, v201, v200, 1.0
	v_mul_f32_e32 v201, 0x3fb8aa3b, v137
	v_exp_f32_e32 v201, v201
	v_fma_f32 v200, v202, v200, 1.0
	v_sqrt_f32_e32 v136, v136
	v_mul_f32_e64 v200, v200, -v137
	v_sub_f32_e32 v201, 1.0, v201
	v_cmp_lt_f32_e32 vcc, -0.5, v137
	v_mul_f32_e32 v136, v198, v136
	v_cvt_pk_bf16_f32 v132, v132, v136
	v_mul_f32_e32 v136, v199, v196
	v_cndmask_b32_e32 v137, v201, v200, vcc
	v_sqrt_f32_e32 v137, v137
	v_add_f32_e32 v134, v134, v110
	v_mul_f32_e32 v134, 0xbfb8aa3b, v134
	v_exp_f32_e32 v134, v134
	v_mul_f32_e32 v136, v136, v137
	v_cvt_pk_bf16_f32 v133, v133, v136
	v_add_f32_e32 v136, v138, v114
	v_mul_f32_e32 v136, 0xbfb8aa3b, v136
	v_exp_f32_e32 v136, v136
	v_add_f32_e32 v134, 1.0, v134
	v_rcp_f32_e32 v137, v134
	v_add_f32_e32 v135, v135, v111
	v_add_f32_e32 v134, 1.0, v136
	v_add_f32_e32 v136, v139, v115
	v_mul_f32_e32 v136, 0xbfb8aa3b, v136
	v_exp_f32_e32 v136, v136
	v_lshlrev_b32_e32 v138, 16, v197
	v_mul_f32_e32 v135, 0xbfb8aa3b, v135
	v_mul_f32_e32 v138, v137, v138
	v_exp_f32_e32 v137, v135
	v_add_f32_e32 v135, 1.0, v136
	v_rcp_f32_e32 v134, v134
	v_rcp_f32_e32 v135, v135
	v_add_f32_e32 v136, 1.0, v137
	v_rcp_f32_e32 v196, v136
	v_and_b32_e32 v139, 0xffff0000, v197
	v_pk_mul_f32 v[134:135], v[134:135], s[22:23] op_sel_hi:[1,0]
	v_add_f32_e32 v124, v124, v108
	v_pk_mul_f32 v[134:135], v[106:107], v[134:135]
	v_mul_f32_e32 v124, 0xbfb8aa3b, v124
	v_pk_add_f32 v[136:137], v[134:135], v[134:135]
	v_add_f32_e32 v128, v128, v112
	v_fma_f32 v197, v136, s66, 1.0
	v_mul_f32_e32 v198, 0x3e4ccccd, v136
	v_fma_f32 v197, v198, v197, 1.0
	v_mul_f32_e32 v198, 0x3e800000, v136
	v_fma_f32 v197, v198, v197, 1.0
	v_mul_f32_e32 v198, 0x3eaaaaab, v136
	v_fma_f32 v197, v198, v197, 1.0
	v_mul_f32_e32 v198, 0x3fb8aa3b, v136
	v_exp_f32_e32 v198, v198
	v_mul_f32_e32 v199, 0.5, v136
	v_fma_f32 v197, v199, v197, 1.0
	v_mul_f32_e64 v197, v197, -v136
	v_sub_f32_e32 v198, 1.0, v198
	v_cmp_lt_f32_e32 vcc, -0.5, v136
	v_mul_f32_e32 v199, 0.5, v137
	v_exp_f32_e32 v124, v124
	v_cndmask_b32_e32 v136, v198, v197, vcc
	v_fma_f32 v197, v137, s66, 1.0
	v_mul_f32_e32 v198, 0x3e4ccccd, v137
	v_fma_f32 v197, v198, v197, 1.0
	v_mul_f32_e32 v198, 0x3e800000, v137
	v_fma_f32 v197, v198, v197, 1.0
	v_mul_f32_e32 v198, 0x3eaaaaab, v137
	v_fma_f32 v197, v198, v197, 1.0
	v_mul_f32_e32 v198, 0x3fb8aa3b, v137
	v_exp_f32_e32 v198, v198
	v_fma_f32 v197, v199, v197, 1.0
	v_sqrt_f32_e32 v136, v136
	v_mul_f32_e64 v197, v197, -v137
	v_sub_f32_e32 v198, 1.0, v198
	v_cmp_lt_f32_e32 vcc, -0.5, v137
	v_mul_f32_e32 v128, 0xbfb8aa3b, v128
	v_mul_f32_e32 v136, v138, v136
	v_cndmask_b32_e32 v137, v198, v197, vcc
	v_sqrt_f32_e32 v137, v137
	v_exp_f32_e32 v128, v128
	v_cvt_pk_bf16_f32 v134, v134, v136
	v_mul_f32_e32 v136, v196, v139
	v_mul_f32_e32 v136, v136, v137
	v_cvt_pk_bf16_f32 v135, v135, v136
	v_lshl_add_u64 v[136:137], v[148:149], 2, s[72:73]
	v_add_f32_e32 v124, 1.0, v124
	global_store_dwordx4 v[136:137], v[132:135], off
	v_add_f32_e32 v125, v125, v109
	v_mul_f32_e32 v125, 0xbfb8aa3b, v125
	v_rcp_f32_e32 v132, v124
	v_add_f32_e32 v124, 1.0, v128
	v_add_f32_e32 v128, v129, v113
	v_mul_f32_e32 v128, 0xbfb8aa3b, v128
	v_exp_f32_e32 v128, v128
	v_exp_f32_e32 v129, v125
	v_rcp_f32_e32 v124, v124
	v_lshlrev_b32_e32 v133, 16, v188
	v_add_f32_e32 v125, 1.0, v128
	v_rcp_f32_e32 v125, v125
	v_add_f32_e32 v128, 1.0, v129
	v_rcp_f32_e32 v134, v128
	v_mul_f32_e32 v132, v132, v133
	v_pk_mul_f32 v[124:125], v[124:125], s[22:23] op_sel_hi:[1,0]
	v_and_b32_e32 v133, 0xffff0000, v188
	v_pk_mul_f32 v[124:125], v[104:105], v[124:125]
	v_add_f32_e32 v126, v126, v110
	v_pk_add_f32 v[128:129], v[124:125], v[124:125]
	v_mul_f32_e32 v126, 0xbfb8aa3b, v126
	v_fma_f32 v135, v128, s66, 1.0
	v_mul_f32_e32 v136, 0x3e4ccccd, v128
	v_fma_f32 v135, v136, v135, 1.0
	v_mul_f32_e32 v136, 0x3e800000, v128
	v_fma_f32 v135, v136, v135, 1.0
	v_mul_f32_e32 v136, 0x3eaaaaab, v128
	v_fma_f32 v135, v136, v135, 1.0
	v_mul_f32_e32 v136, 0x3fb8aa3b, v128
	v_exp_f32_e32 v136, v136
	v_mul_f32_e32 v137, 0.5, v128
	v_fma_f32 v135, v137, v135, 1.0
	v_mul_f32_e64 v135, v135, -v128
	v_sub_f32_e32 v136, 1.0, v136
	v_cmp_lt_f32_e32 vcc, -0.5, v128
	v_mul_f32_e32 v137, 0.5, v129
	v_exp_f32_e32 v126, v126
	v_cndmask_b32_e32 v128, v136, v135, vcc
	v_fma_f32 v135, v129, s66, 1.0
	v_mul_f32_e32 v136, 0x3e4ccccd, v129
	v_fma_f32 v135, v136, v135, 1.0
	v_mul_f32_e32 v136, 0x3e800000, v129
	v_fma_f32 v135, v136, v135, 1.0
	v_mul_f32_e32 v136, 0x3eaaaaab, v129
	v_fma_f32 v135, v136, v135, 1.0
	v_mul_f32_e32 v136, 0x3fb8aa3b, v129
	v_exp_f32_e32 v136, v136
	v_fma_f32 v135, v137, v135, 1.0
	v_sqrt_f32_e32 v128, v128
	v_mul_f32_e64 v135, v135, -v129
	v_sub_f32_e32 v136, 1.0, v136
	v_cmp_lt_f32_e32 vcc, -0.5, v129
	v_mul_f32_e32 v128, v132, v128
	v_cvt_pk_bf16_f32 v124, v124, v128
	v_mul_f32_e32 v128, v134, v133
	v_cndmask_b32_e32 v129, v136, v135, vcc
	v_sqrt_f32_e32 v129, v129
	v_add_f32_e32 v126, 1.0, v126
	v_add_f32_e32 v127, v127, v111
	v_mul_f32_e32 v127, 0xbfb8aa3b, v127
	v_mul_f32_e32 v128, v128, v129
	v_cvt_pk_bf16_f32 v125, v125, v128
	v_add_f32_e32 v128, v130, v114
	v_mul_f32_e32 v128, 0xbfb8aa3b, v128
	v_exp_f32_e32 v128, v128
	v_rcp_f32_e32 v129, v126
	v_lshlrev_b32_e32 v130, 16, v189
	v_add_f32_e32 v116, v116, v108
	v_add_f32_e32 v126, 1.0, v128
	v_add_f32_e32 v128, v131, v115
	v_mul_f32_e32 v128, 0xbfb8aa3b, v128
	v_exp_f32_e32 v128, v128
	v_mul_f32_e32 v130, v129, v130
	v_exp_f32_e32 v129, v127
	v_rcp_f32_e32 v126, v126
	v_add_f32_e32 v127, 1.0, v128
	v_rcp_f32_e32 v127, v127
	v_add_f32_e32 v128, 1.0, v129
	v_rcp_f32_e32 v132, v128
	v_mul_f32_e32 v116, 0xbfb8aa3b, v116
	v_pk_mul_f32 v[126:127], v[126:127], s[22:23] op_sel_hi:[1,0]
	v_add_f32_e32 v120, v120, v112
	v_pk_mul_f32 v[126:127], v[106:107], v[126:127]
	v_and_b32_e32 v131, 0xffff0000, v189
	v_pk_add_f32 v[128:129], v[126:127], v[126:127]
	v_exp_f32_e32 v116, v116
	v_fma_f32 v133, v128, s66, 1.0
	v_mul_f32_e32 v134, 0x3e4ccccd, v128
	v_fma_f32 v133, v134, v133, 1.0
	v_mul_f32_e32 v134, 0x3e800000, v128
	v_fma_f32 v133, v134, v133, 1.0
	v_mul_f32_e32 v134, 0x3eaaaaab, v128
	v_fma_f32 v133, v134, v133, 1.0
	v_mul_f32_e32 v134, 0x3fb8aa3b, v128
	v_exp_f32_e32 v134, v134
	v_mul_f32_e32 v135, 0.5, v128
	v_fma_f32 v133, v135, v133, 1.0
	v_mul_f32_e64 v133, v133, -v128
	v_sub_f32_e32 v134, 1.0, v134
	v_cmp_lt_f32_e32 vcc, -0.5, v128
	v_mul_f32_e32 v135, 0.5, v129
	v_mul_f32_e32 v120, 0xbfb8aa3b, v120
	v_cndmask_b32_e32 v128, v134, v133, vcc
	v_fma_f32 v133, v129, s66, 1.0
	v_mul_f32_e32 v134, 0x3e4ccccd, v129
	v_fma_f32 v133, v134, v133, 1.0
	v_mul_f32_e32 v134, 0x3e800000, v129
	v_fma_f32 v133, v134, v133, 1.0
	v_mul_f32_e32 v134, 0x3eaaaaab, v129
	v_fma_f32 v133, v134, v133, 1.0
	v_mul_f32_e32 v134, 0x3fb8aa3b, v129
	v_exp_f32_e32 v134, v134
	v_fma_f32 v133, v135, v133, 1.0
	v_sqrt_f32_e32 v128, v128
	v_mul_f32_e64 v133, v133, -v129
	v_sub_f32_e32 v134, 1.0, v134
	v_cmp_lt_f32_e32 vcc, -0.5, v129
	v_mul_f32_e32 v128, v130, v128
	v_cvt_pk_bf16_f32 v126, v126, v128
	v_mul_f32_e32 v128, v132, v131
	v_cndmask_b32_e32 v129, v134, v133, vcc
	v_sqrt_f32_e32 v129, v129
	v_exp_f32_e32 v120, v120
	v_add_f32_e32 v116, 1.0, v116
	v_add_f32_e32 v117, v117, v109
	v_mul_f32_e32 v128, v128, v129
	v_cvt_pk_bf16_f32 v127, v127, v128
	v_add_u32_e32 v128, 0x8000, v148
	v_mov_b32_e32 v129, v149
	v_lshl_add_u64 v[128:129], v[128:129], 2, s[72:73]
	global_store_dwordx4 v[128:129], v[124:127], off
	v_mul_f32_e32 v117, 0xbfb8aa3b, v117
	v_add_f32_e32 v118, v118, v110
	v_rcp_f32_e32 v124, v116
	v_add_f32_e32 v116, 1.0, v120
	v_add_f32_e32 v120, v121, v113
	v_mul_f32_e32 v120, 0xbfb8aa3b, v120
	v_exp_f32_e32 v120, v120
	v_exp_f32_e32 v121, v117
	v_rcp_f32_e32 v116, v116
	v_lshlrev_b32_e32 v125, 16, v186
	v_add_f32_e32 v117, 1.0, v120
	v_rcp_f32_e32 v117, v117
	v_add_f32_e32 v120, 1.0, v121
	v_rcp_f32_e32 v126, v120
	v_mul_f32_e32 v124, v124, v125
	v_pk_mul_f32 v[116:117], v[116:117], s[22:23] op_sel_hi:[1,0]
	v_and_b32_e32 v125, 0xffff0000, v186
	v_pk_mul_f32 v[116:117], v[104:105], v[116:117]
	v_mul_f32_e32 v118, 0xbfb8aa3b, v118
	v_pk_add_f32 v[120:121], v[116:117], v[116:117]
	v_exp_f32_e32 v118, v118
	v_fma_f32 v127, v120, s66, 1.0
	v_mul_f32_e32 v128, 0x3e4ccccd, v120
	v_fma_f32 v127, v128, v127, 1.0
	v_mul_f32_e32 v128, 0x3e800000, v120
	v_fma_f32 v127, v128, v127, 1.0
	v_mul_f32_e32 v128, 0x3eaaaaab, v120
	v_fma_f32 v127, v128, v127, 1.0
	v_mul_f32_e32 v128, 0x3fb8aa3b, v120
	v_exp_f32_e32 v128, v128
	v_mul_f32_e32 v129, 0.5, v120
	v_fma_f32 v127, v129, v127, 1.0
	v_mul_f32_e64 v127, v127, -v120
	v_sub_f32_e32 v128, 1.0, v128
	v_cmp_lt_f32_e32 vcc, -0.5, v120
	v_mul_f32_e32 v129, 0.5, v121
	v_add_f32_e32 v118, 1.0, v118
	v_cndmask_b32_e32 v120, v128, v127, vcc
	v_fma_f32 v127, v121, s66, 1.0
	v_mul_f32_e32 v128, 0x3e4ccccd, v121
	v_fma_f32 v127, v128, v127, 1.0
	v_mul_f32_e32 v128, 0x3e800000, v121
	v_fma_f32 v127, v128, v127, 1.0
	v_mul_f32_e32 v128, 0x3eaaaaab, v121
	v_fma_f32 v127, v128, v127, 1.0
	v_mul_f32_e32 v128, 0x3fb8aa3b, v121
	v_exp_f32_e32 v128, v128
	v_fma_f32 v127, v129, v127, 1.0
	v_sqrt_f32_e32 v120, v120
	v_mul_f32_e64 v127, v127, -v121
	v_sub_f32_e32 v128, 1.0, v128
	v_cmp_lt_f32_e32 vcc, -0.5, v121
	v_mul_f32_e32 v120, v124, v120
	v_cvt_pk_bf16_f32 v116, v116, v120
	v_mul_f32_e32 v120, v126, v125
	v_cndmask_b32_e32 v121, v128, v127, vcc
	v_sqrt_f32_e32 v121, v121
	v_add_f32_e32 v119, v119, v111
	v_mul_f32_e32 v119, 0xbfb8aa3b, v119
	v_add_f32_e32 v96, v96, v108
	v_mul_f32_e32 v120, v120, v121
	v_cvt_pk_bf16_f32 v117, v117, v120
	v_add_f32_e32 v120, v122, v114
	v_mul_f32_e32 v120, 0xbfb8aa3b, v120
	v_exp_f32_e32 v120, v120
	v_rcp_f32_e32 v121, v118
	v_lshlrev_b32_e32 v122, 16, v187
	v_mul_f32_e32 v96, 0xbfb8aa3b, v96
	v_add_f32_e32 v118, 1.0, v120
	v_add_f32_e32 v120, v123, v115
	v_mul_f32_e32 v120, 0xbfb8aa3b, v120
	v_exp_f32_e32 v120, v120
	v_mul_f32_e32 v122, v121, v122
	v_exp_f32_e32 v121, v119
	v_rcp_f32_e32 v118, v118
	v_add_f32_e32 v119, 1.0, v120
	v_rcp_f32_e32 v119, v119
	v_add_f32_e32 v120, 1.0, v121
	v_rcp_f32_e32 v124, v120
	v_add_f32_e32 v100, v100, v112
	v_pk_mul_f32 v[118:119], v[118:119], s[22:23] op_sel_hi:[1,0]
	v_and_b32_e32 v123, 0xffff0000, v187
	v_pk_mul_f32 v[118:119], v[106:107], v[118:119]
	v_exp_f32_e32 v96, v96
	v_pk_add_f32 v[120:121], v[118:119], v[118:119]
	v_mul_f32_e32 v100, 0xbfb8aa3b, v100
	v_fma_f32 v125, v120, s66, 1.0
	v_mul_f32_e32 v126, 0x3e4ccccd, v120
	v_fma_f32 v125, v126, v125, 1.0
	v_mul_f32_e32 v126, 0x3e800000, v120
	v_fma_f32 v125, v126, v125, 1.0
	v_mul_f32_e32 v126, 0x3eaaaaab, v120
	v_fma_f32 v125, v126, v125, 1.0
	v_mul_f32_e32 v126, 0x3fb8aa3b, v120
	v_exp_f32_e32 v126, v126
	v_mul_f32_e32 v127, 0.5, v120
	v_fma_f32 v125, v127, v125, 1.0
	v_mul_f32_e64 v125, v125, -v120
	v_sub_f32_e32 v126, 1.0, v126
	v_cmp_lt_f32_e32 vcc, -0.5, v120
	v_mul_f32_e32 v127, 0.5, v121
	v_exp_f32_e32 v100, v100
	v_cndmask_b32_e32 v120, v126, v125, vcc
	v_fma_f32 v125, v121, s66, 1.0
	v_mul_f32_e32 v126, 0x3e4ccccd, v121
	v_fma_f32 v125, v126, v125, 1.0
	v_mul_f32_e32 v126, 0x3e800000, v121
	v_fma_f32 v125, v126, v125, 1.0
	v_mul_f32_e32 v126, 0x3eaaaaab, v121
	v_fma_f32 v125, v126, v125, 1.0
	v_mul_f32_e32 v126, 0x3fb8aa3b, v121
	v_exp_f32_e32 v126, v126
	v_fma_f32 v125, v127, v125, 1.0
	v_sqrt_f32_e32 v120, v120
	v_mul_f32_e64 v125, v125, -v121
	v_sub_f32_e32 v126, 1.0, v126
	v_cmp_lt_f32_e32 vcc, -0.5, v121
	v_mul_f32_e32 v120, v122, v120
	v_cvt_pk_bf16_f32 v118, v118, v120
	v_mul_f32_e32 v120, v124, v123
	v_cndmask_b32_e32 v121, v126, v125, vcc
	v_sqrt_f32_e32 v121, v121
	v_add_f32_e32 v96, 1.0, v96
	v_add_f32_e32 v97, v97, v109
	v_mul_f32_e32 v97, 0xbfb8aa3b, v97
	v_mul_f32_e32 v120, v120, v121
	v_cvt_pk_bf16_f32 v119, v119, v120
	v_add_u32_e32 v120, 0x10000, v148
	v_mov_b32_e32 v121, v149
	v_lshl_add_u64 v[120:121], v[120:121], 2, s[72:73]
	global_store_dwordx4 v[120:121], v[116:119], off
	v_add_f32_e32 v98, v98, v110
	v_mul_f32_e32 v98, 0xbfb8aa3b, v98
	v_rcp_f32_e32 v116, v96
	v_add_f32_e32 v96, 1.0, v100
	v_add_f32_e32 v100, v101, v113
	v_mul_f32_e32 v100, 0xbfb8aa3b, v100
	v_exp_f32_e32 v100, v100
	v_exp_f32_e32 v101, v97
	v_rcp_f32_e32 v96, v96
	v_lshlrev_b32_e32 v117, 16, v182
	v_add_f32_e32 v97, 1.0, v100
	v_rcp_f32_e32 v97, v97
	v_add_f32_e32 v100, 1.0, v101
	v_rcp_f32_e32 v118, v100
	v_mul_f32_e32 v116, v116, v117
	v_pk_mul_f32 v[96:97], v[96:97], s[22:23] op_sel_hi:[1,0]
	v_and_b32_e32 v117, 0xffff0000, v182
	v_pk_mul_f32 v[96:97], v[104:105], v[96:97]
	v_exp_f32_e32 v98, v98
	v_pk_add_f32 v[100:101], v[96:97], v[96:97]
	v_add_f32_e32 v99, v99, v111
	v_fma_f32 v119, v100, s66, 1.0
	v_mul_f32_e32 v120, 0x3e4ccccd, v100
	v_fma_f32 v119, v120, v119, 1.0
	v_mul_f32_e32 v120, 0x3e800000, v100
	v_fma_f32 v119, v120, v119, 1.0
	v_mul_f32_e32 v120, 0x3eaaaaab, v100
	v_fma_f32 v119, v120, v119, 1.0
	v_mul_f32_e32 v120, 0x3fb8aa3b, v100
	v_exp_f32_e32 v120, v120
	v_mul_f32_e32 v121, 0.5, v100
	v_fma_f32 v119, v121, v119, 1.0
	v_mul_f32_e64 v119, v119, -v100
	v_sub_f32_e32 v120, 1.0, v120
	v_cmp_lt_f32_e32 vcc, -0.5, v100
	v_mul_f32_e32 v121, 0.5, v101
	v_add_f32_e32 v98, 1.0, v98
	v_cndmask_b32_e32 v100, v120, v119, vcc
	v_fma_f32 v119, v101, s66, 1.0
	v_mul_f32_e32 v120, 0x3e4ccccd, v101
	v_fma_f32 v119, v120, v119, 1.0
	v_mul_f32_e32 v120, 0x3e800000, v101
	v_fma_f32 v119, v120, v119, 1.0
	v_mul_f32_e32 v120, 0x3eaaaaab, v101
	v_fma_f32 v119, v120, v119, 1.0
	v_mul_f32_e32 v120, 0x3fb8aa3b, v101
	v_exp_f32_e32 v120, v120
	v_fma_f32 v119, v121, v119, 1.0
	v_sqrt_f32_e32 v100, v100
	v_mul_f32_e64 v119, v119, -v101
	v_sub_f32_e32 v120, 1.0, v120
	v_cmp_lt_f32_e32 vcc, -0.5, v101
	v_mul_f32_e32 v100, v116, v100
	v_cvt_pk_bf16_f32 v96, v96, v100
	v_mul_f32_e32 v100, v118, v117
	v_cndmask_b32_e32 v101, v120, v119, vcc
	v_sqrt_f32_e32 v101, v101
	v_mul_f32_e32 v99, 0xbfb8aa3b, v99
	v_add_f32_e32 v88, v88, v108
	v_mul_f32_e32 v88, 0xbfb8aa3b, v88
	v_mul_f32_e32 v100, v100, v101
	v_cvt_pk_bf16_f32 v97, v97, v100
	v_add_f32_e32 v100, v102, v114
	v_mul_f32_e32 v100, 0xbfb8aa3b, v100
	v_exp_f32_e32 v100, v100
	v_rcp_f32_e32 v101, v98
	v_lshlrev_b32_e32 v102, 16, v183
	v_add_f32_e32 v92, v92, v112
	v_add_f32_e32 v98, 1.0, v100
	v_add_f32_e32 v100, v103, v115
	v_mul_f32_e32 v100, 0xbfb8aa3b, v100
	v_exp_f32_e32 v100, v100
	v_mul_f32_e32 v102, v101, v102
	v_exp_f32_e32 v101, v99
	v_rcp_f32_e32 v98, v98
	v_add_f32_e32 v99, 1.0, v100
	v_rcp_f32_e32 v99, v99
	v_add_f32_e32 v100, 1.0, v101
	v_rcp_f32_e32 v116, v100
	v_and_b32_e32 v103, 0xffff0000, v183
	v_pk_mul_f32 v[98:99], v[98:99], s[22:23] op_sel_hi:[1,0]
	v_exp_f32_e32 v88, v88
	v_pk_mul_f32 v[98:99], v[106:107], v[98:99]
	v_mul_f32_e32 v92, 0xbfb8aa3b, v92
	v_pk_add_f32 v[100:101], v[98:99], v[98:99]
	v_exp_f32_e32 v92, v92
	v_fma_f32 v117, v100, s66, 1.0
	v_mul_f32_e32 v118, 0x3e4ccccd, v100
	v_fma_f32 v117, v118, v117, 1.0
	v_mul_f32_e32 v118, 0x3e800000, v100
	v_fma_f32 v117, v118, v117, 1.0
	v_mul_f32_e32 v118, 0x3eaaaaab, v100
	v_fma_f32 v117, v118, v117, 1.0
	v_mul_f32_e32 v118, 0x3fb8aa3b, v100
	v_exp_f32_e32 v118, v118
	v_mul_f32_e32 v119, 0.5, v100
	v_fma_f32 v117, v119, v117, 1.0
	v_mul_f32_e64 v117, v117, -v100
	v_sub_f32_e32 v118, 1.0, v118
	v_cmp_lt_f32_e32 vcc, -0.5, v100
	v_mul_f32_e32 v119, 0.5, v101
	v_add_f32_e32 v88, 1.0, v88
	v_cndmask_b32_e32 v100, v118, v117, vcc
	v_fma_f32 v117, v101, s66, 1.0
	v_mul_f32_e32 v118, 0x3e4ccccd, v101
	v_fma_f32 v117, v118, v117, 1.0
	v_mul_f32_e32 v118, 0x3e800000, v101
	v_fma_f32 v117, v118, v117, 1.0
	v_mul_f32_e32 v118, 0x3eaaaaab, v101
	v_fma_f32 v117, v118, v117, 1.0
	v_mul_f32_e32 v118, 0x3fb8aa3b, v101
	v_exp_f32_e32 v118, v118
	v_fma_f32 v117, v119, v117, 1.0
	v_sqrt_f32_e32 v100, v100
	v_mul_f32_e64 v117, v117, -v101
	v_sub_f32_e32 v118, 1.0, v118
	v_cmp_lt_f32_e32 vcc, -0.5, v101
	v_mul_f32_e32 v100, v102, v100
	v_cvt_pk_bf16_f32 v98, v98, v100
	v_mul_f32_e32 v100, v116, v103
	v_cndmask_b32_e32 v101, v118, v117, vcc
	v_sqrt_f32_e32 v101, v101
	v_add_f32_e32 v89, v89, v109
	v_mul_f32_e32 v89, 0xbfb8aa3b, v89
	v_add_f32_e32 v90, v90, v110
	v_mul_f32_e32 v100, v100, v101
	v_cvt_pk_bf16_f32 v99, v99, v100
	v_add_u32_e32 v100, 0x18000, v148
	v_mov_b32_e32 v101, v149
	v_lshl_add_u64 v[100:101], v[100:101], 2, s[72:73]
	global_store_dwordx4 v[100:101], v[96:99], off
	v_mul_f32_e32 v90, 0xbfb8aa3b, v90
	v_exp_f32_e32 v90, v90
	v_rcp_f32_e32 v97, v88
	v_add_f32_e32 v88, 1.0, v92
	v_add_f32_e32 v92, v93, v113
	v_mul_f32_e32 v92, 0xbfb8aa3b, v92
	v_exp_f32_e32 v92, v92
	v_exp_f32_e32 v93, v89
	v_rcp_f32_e32 v88, v88
	v_lshlrev_b32_e32 v98, 16, v180
	v_add_f32_e32 v89, 1.0, v92
	v_rcp_f32_e32 v89, v89
	v_add_f32_e32 v92, 1.0, v93
	v_rcp_f32_e32 v99, v92
	v_mul_f32_e32 v97, v97, v98
	v_pk_mul_f32 v[88:89], v[88:89], s[22:23] op_sel_hi:[1,0]
	v_and_b32_e32 v98, 0xffff0000, v180
	v_pk_mul_f32 v[88:89], v[104:105], v[88:89]
	v_add_f32_e32 v90, 1.0, v90
	v_pk_add_f32 v[92:93], v[88:89], v[88:89]
	v_add_f32_e32 v91, v91, v111
	v_fma_f32 v100, v92, s66, 1.0
	v_mul_f32_e32 v101, 0x3e4ccccd, v92
	v_fma_f32 v100, v101, v100, 1.0
	v_mul_f32_e32 v101, 0x3e800000, v92
	v_fma_f32 v100, v101, v100, 1.0
	v_mul_f32_e32 v101, 0x3eaaaaab, v92
	v_fma_f32 v100, v101, v100, 1.0
	v_mul_f32_e32 v101, 0x3fb8aa3b, v92
	v_exp_f32_e32 v101, v101
	v_mul_f32_e32 v102, 0.5, v92
	v_fma_f32 v100, v102, v100, 1.0
	v_mul_f32_e64 v100, v100, -v92
	v_sub_f32_e32 v101, 1.0, v101
	v_cmp_lt_f32_e32 vcc, -0.5, v92
	v_mul_f32_e32 v102, 0.5, v93
	v_mul_f32_e32 v91, 0xbfb8aa3b, v91
	v_cndmask_b32_e32 v92, v101, v100, vcc
	v_fma_f32 v100, v93, s66, 1.0
	v_mul_f32_e32 v101, 0x3e4ccccd, v93
	v_fma_f32 v100, v101, v100, 1.0
	v_mul_f32_e32 v101, 0x3e800000, v93
	v_fma_f32 v100, v101, v100, 1.0
	v_mul_f32_e32 v101, 0x3eaaaaab, v93
	v_fma_f32 v100, v101, v100, 1.0
	v_mul_f32_e32 v101, 0x3fb8aa3b, v93
	v_exp_f32_e32 v101, v101
	v_fma_f32 v100, v102, v100, 1.0
	v_sqrt_f32_e32 v92, v92
	v_mul_f32_e64 v100, v100, -v93
	v_sub_f32_e32 v101, 1.0, v101
	v_cmp_lt_f32_e32 vcc, -0.5, v93
	v_mul_f32_e32 v92, v97, v92
	v_cvt_pk_bf16_f32 v88, v88, v92
	v_mul_f32_e32 v92, v99, v98
	v_cndmask_b32_e32 v93, v101, v100, vcc
	v_sqrt_f32_e32 v93, v93
	v_add_f32_e32 v80, v80, v108
	v_mul_f32_e32 v80, 0xbfb8aa3b, v80
	v_add_f32_e32 v84, v84, v112
	v_mul_f32_e32 v92, v92, v93
	v_cvt_pk_bf16_f32 v89, v89, v92
	v_add_f32_e32 v92, v94, v114
	v_mul_f32_e32 v92, 0xbfb8aa3b, v92
	v_exp_f32_e32 v92, v92
	v_rcp_f32_e32 v93, v90
	v_lshlrev_b32_e32 v94, 16, v181
	v_exp_f32_e32 v80, v80
	v_add_f32_e32 v90, 1.0, v92
	v_add_f32_e32 v92, v95, v115
	v_mul_f32_e32 v92, 0xbfb8aa3b, v92
	v_exp_f32_e32 v92, v92
	v_mul_f32_e32 v94, v93, v94
	v_exp_f32_e32 v93, v91
	v_rcp_f32_e32 v90, v90
	v_add_f32_e32 v91, 1.0, v92
	v_rcp_f32_e32 v91, v91
	v_add_f32_e32 v92, 1.0, v93
	v_rcp_f32_e32 v97, v92
	v_mul_f32_e32 v84, 0xbfb8aa3b, v84
	v_pk_mul_f32 v[90:91], v[90:91], s[22:23] op_sel_hi:[1,0]
	v_and_b32_e32 v95, 0xffff0000, v181
	v_pk_mul_f32 v[90:91], v[106:107], v[90:91]
	v_exp_f32_e32 v84, v84
	v_pk_add_f32 v[92:93], v[90:91], v[90:91]
	v_add_u32_e32 v96, 0x40000, v148
	v_fma_f32 v98, v92, s66, 1.0
	v_mul_f32_e32 v99, 0x3e4ccccd, v92
	v_fma_f32 v98, v99, v98, 1.0
	v_mul_f32_e32 v99, 0x3e800000, v92
	v_fma_f32 v98, v99, v98, 1.0
	v_mul_f32_e32 v99, 0x3eaaaaab, v92
	v_fma_f32 v98, v99, v98, 1.0
	v_mul_f32_e32 v99, 0x3fb8aa3b, v92
	v_exp_f32_e32 v99, v99
	v_mul_f32_e32 v100, 0.5, v92
	v_fma_f32 v98, v100, v98, 1.0
	v_mul_f32_e64 v98, v98, -v92
	v_sub_f32_e32 v99, 1.0, v99
	v_cmp_lt_f32_e32 vcc, -0.5, v92
	v_mul_f32_e32 v100, 0.5, v93
	v_add_f32_e32 v80, 1.0, v80
	v_cndmask_b32_e32 v92, v99, v98, vcc
	v_fma_f32 v98, v93, s66, 1.0
	v_mul_f32_e32 v99, 0x3e4ccccd, v93
	v_fma_f32 v98, v99, v98, 1.0
	v_mul_f32_e32 v99, 0x3e800000, v93
	v_fma_f32 v98, v99, v98, 1.0
	v_mul_f32_e32 v99, 0x3eaaaaab, v93
	v_fma_f32 v98, v99, v98, 1.0
	v_mul_f32_e32 v99, 0x3fb8aa3b, v93
	v_exp_f32_e32 v99, v99
	v_fma_f32 v98, v100, v98, 1.0
	v_sqrt_f32_e32 v92, v92
	v_mul_f32_e64 v98, v98, -v93
	v_sub_f32_e32 v99, 1.0, v99
	v_cmp_lt_f32_e32 vcc, -0.5, v93
	v_mul_f32_e32 v92, v94, v92
	v_cvt_pk_bf16_f32 v90, v90, v92
	v_mul_f32_e32 v92, v97, v95
	v_cndmask_b32_e32 v93, v99, v98, vcc
	v_sqrt_f32_e32 v93, v93
	v_mov_b32_e32 v97, v149
	v_add_f32_e32 v81, v81, v109
	v_mul_f32_e32 v81, 0xbfb8aa3b, v81
	v_mul_f32_e32 v92, v92, v93
	v_cvt_pk_bf16_f32 v91, v91, v92
	v_lshl_add_u64 v[92:93], v[96:97], 2, s[72:73]
	global_store_dwordx4 v[92:93], v[88:91], off
	v_add_f32_e32 v82, v82, v110
	v_mul_f32_e32 v82, 0xbfb8aa3b, v82
	v_rcp_f32_e32 v88, v80
	v_add_f32_e32 v80, 1.0, v84
	v_add_f32_e32 v84, v85, v113
	v_mul_f32_e32 v84, 0xbfb8aa3b, v84
	v_exp_f32_e32 v84, v84
	v_exp_f32_e32 v85, v81
	v_rcp_f32_e32 v80, v80
	v_lshlrev_b32_e32 v89, 16, v178
	v_add_f32_e32 v81, 1.0, v84
	v_rcp_f32_e32 v81, v81
	v_add_f32_e32 v84, 1.0, v85
	v_rcp_f32_e32 v90, v84
	v_mul_f32_e32 v88, v88, v89
	v_pk_mul_f32 v[80:81], v[80:81], s[22:23] op_sel_hi:[1,0]
	v_and_b32_e32 v89, 0xffff0000, v178
	v_pk_mul_f32 v[80:81], v[104:105], v[80:81]
	v_exp_f32_e32 v82, v82
	v_pk_add_f32 v[84:85], v[80:81], v[80:81]
	v_add_f32_e32 v83, v83, v111
	v_fma_f32 v91, v84, s66, 1.0
	v_mul_f32_e32 v92, 0x3e4ccccd, v84
	v_fma_f32 v91, v92, v91, 1.0
	v_mul_f32_e32 v92, 0x3e800000, v84
	v_fma_f32 v91, v92, v91, 1.0
	v_mul_f32_e32 v92, 0x3eaaaaab, v84
	v_fma_f32 v91, v92, v91, 1.0
	v_mul_f32_e32 v92, 0x3fb8aa3b, v84
	v_exp_f32_e32 v92, v92
	v_mul_f32_e32 v93, 0.5, v84
	v_fma_f32 v91, v93, v91, 1.0
	v_mul_f32_e64 v91, v91, -v84
	v_sub_f32_e32 v92, 1.0, v92
	v_cmp_lt_f32_e32 vcc, -0.5, v84
	v_mul_f32_e32 v93, 0.5, v85
	v_add_f32_e32 v82, 1.0, v82
	v_cndmask_b32_e32 v84, v92, v91, vcc
	v_fma_f32 v91, v85, s66, 1.0
	v_mul_f32_e32 v92, 0x3e4ccccd, v85
	v_fma_f32 v91, v92, v91, 1.0
	v_mul_f32_e32 v92, 0x3e800000, v85
	v_fma_f32 v91, v92, v91, 1.0
	v_mul_f32_e32 v92, 0x3eaaaaab, v85
	v_fma_f32 v91, v92, v91, 1.0
	v_mul_f32_e32 v92, 0x3fb8aa3b, v85
	v_exp_f32_e32 v92, v92
	v_fma_f32 v91, v93, v91, 1.0
	v_sqrt_f32_e32 v84, v84
	v_mul_f32_e64 v91, v91, -v85
	v_sub_f32_e32 v92, 1.0, v92
	v_cmp_lt_f32_e32 vcc, -0.5, v85
	v_mul_f32_e32 v84, v88, v84
	v_cvt_pk_bf16_f32 v80, v80, v84
	v_mul_f32_e32 v84, v90, v89
	v_cndmask_b32_e32 v85, v92, v91, vcc
	v_sqrt_f32_e32 v85, v85
	v_mul_f32_e32 v83, 0xbfb8aa3b, v83
	v_add_f32_e32 v72, v72, v108
	v_mul_f32_e32 v72, 0xbfb8aa3b, v72
	v_mul_f32_e32 v84, v84, v85
	v_cvt_pk_bf16_f32 v81, v81, v84
	v_add_f32_e32 v84, v86, v114
	v_mul_f32_e32 v84, 0xbfb8aa3b, v84
	v_exp_f32_e32 v84, v84
	v_rcp_f32_e32 v85, v82
	v_lshlrev_b32_e32 v86, 16, v179
	v_add_f32_e32 v76, v76, v112
	v_add_f32_e32 v82, 1.0, v84
	v_add_f32_e32 v84, v87, v115
	v_mul_f32_e32 v84, 0xbfb8aa3b, v84
	v_exp_f32_e32 v84, v84
	v_mul_f32_e32 v86, v85, v86
	v_exp_f32_e32 v85, v83
	v_rcp_f32_e32 v82, v82
	v_add_f32_e32 v83, 1.0, v84
	v_rcp_f32_e32 v83, v83
	v_add_f32_e32 v84, 1.0, v85
	v_rcp_f32_e32 v88, v84
	v_and_b32_e32 v87, 0xffff0000, v179
	v_pk_mul_f32 v[82:83], v[82:83], s[22:23] op_sel_hi:[1,0]
	v_exp_f32_e32 v72, v72
	v_pk_mul_f32 v[82:83], v[106:107], v[82:83]
	v_mul_f32_e32 v76, 0xbfb8aa3b, v76
	v_pk_add_f32 v[84:85], v[82:83], v[82:83]
	v_exp_f32_e32 v76, v76
	v_fma_f32 v89, v84, s66, 1.0
	v_mul_f32_e32 v90, 0x3e4ccccd, v84
	v_fma_f32 v89, v90, v89, 1.0
	v_mul_f32_e32 v90, 0x3e800000, v84
	v_fma_f32 v89, v90, v89, 1.0
	v_mul_f32_e32 v90, 0x3eaaaaab, v84
	v_fma_f32 v89, v90, v89, 1.0
	v_mul_f32_e32 v90, 0x3fb8aa3b, v84
	v_exp_f32_e32 v90, v90
	v_mul_f32_e32 v91, 0.5, v84
	v_fma_f32 v89, v91, v89, 1.0
	v_mul_f32_e64 v89, v89, -v84
	v_sub_f32_e32 v90, 1.0, v90
	v_cmp_lt_f32_e32 vcc, -0.5, v84
	v_mul_f32_e32 v91, 0.5, v85
	v_add_f32_e32 v72, 1.0, v72
	v_cndmask_b32_e32 v84, v90, v89, vcc
	v_fma_f32 v89, v85, s66, 1.0
	v_mul_f32_e32 v90, 0x3e4ccccd, v85
	v_fma_f32 v89, v90, v89, 1.0
	v_mul_f32_e32 v90, 0x3e800000, v85
	v_fma_f32 v89, v90, v89, 1.0
	v_mul_f32_e32 v90, 0x3eaaaaab, v85
	v_fma_f32 v89, v90, v89, 1.0
	v_mul_f32_e32 v90, 0x3fb8aa3b, v85
	v_exp_f32_e32 v90, v90
	v_fma_f32 v89, v91, v89, 1.0
	v_sqrt_f32_e32 v84, v84
	v_mul_f32_e64 v89, v89, -v85
	v_sub_f32_e32 v90, 1.0, v90
	v_cmp_lt_f32_e32 vcc, -0.5, v85
	v_mul_f32_e32 v84, v86, v84
	v_cvt_pk_bf16_f32 v82, v82, v84
	v_mul_f32_e32 v84, v88, v87
	v_cndmask_b32_e32 v85, v90, v89, vcc
	v_sqrt_f32_e32 v85, v85
	v_add_f32_e32 v73, v73, v109
	v_mul_f32_e32 v73, 0xbfb8aa3b, v73
	v_add_f32_e32 v74, v74, v110
	v_mul_f32_e32 v84, v84, v85
	v_cvt_pk_bf16_f32 v83, v83, v84
	v_add_u32_e32 v84, 0x48000, v148
	v_mov_b32_e32 v85, v149
	v_lshl_add_u64 v[84:85], v[84:85], 2, s[72:73]
	global_store_dwordx4 v[84:85], v[80:83], off
	v_mul_f32_e32 v74, 0xbfb8aa3b, v74
	v_exp_f32_e32 v74, v74
	v_rcp_f32_e32 v80, v72
	v_add_f32_e32 v72, 1.0, v76
	v_add_f32_e32 v76, v77, v113
	v_mul_f32_e32 v76, 0xbfb8aa3b, v76
	v_exp_f32_e32 v76, v76
	v_exp_f32_e32 v77, v73
	v_rcp_f32_e32 v72, v72
	v_lshlrev_b32_e32 v81, 16, v176
	v_add_f32_e32 v73, 1.0, v76
	v_rcp_f32_e32 v73, v73
	v_add_f32_e32 v76, 1.0, v77
	v_rcp_f32_e32 v82, v76
	v_mul_f32_e32 v80, v80, v81
	v_pk_mul_f32 v[72:73], v[72:73], s[22:23] op_sel_hi:[1,0]
	v_and_b32_e32 v81, 0xffff0000, v176
	v_pk_mul_f32 v[72:73], v[104:105], v[72:73]
	v_add_f32_e32 v74, 1.0, v74
	v_pk_add_f32 v[76:77], v[72:73], v[72:73]
	v_add_f32_e32 v75, v75, v111
	v_fma_f32 v83, v76, s66, 1.0
	v_mul_f32_e32 v84, 0x3e4ccccd, v76
	v_fma_f32 v83, v84, v83, 1.0
	v_mul_f32_e32 v84, 0x3e800000, v76
	v_fma_f32 v83, v84, v83, 1.0
	v_mul_f32_e32 v84, 0x3eaaaaab, v76
	v_fma_f32 v83, v84, v83, 1.0
	v_mul_f32_e32 v84, 0x3fb8aa3b, v76
	v_exp_f32_e32 v84, v84
	v_mul_f32_e32 v85, 0.5, v76
	v_fma_f32 v83, v85, v83, 1.0
	v_mul_f32_e64 v83, v83, -v76
	v_sub_f32_e32 v84, 1.0, v84
	v_cmp_lt_f32_e32 vcc, -0.5, v76
	v_mul_f32_e32 v85, 0.5, v77
	v_mul_f32_e32 v75, 0xbfb8aa3b, v75
	v_cndmask_b32_e32 v76, v84, v83, vcc
	v_fma_f32 v83, v77, s66, 1.0
	v_mul_f32_e32 v84, 0x3e4ccccd, v77
	v_fma_f32 v83, v84, v83, 1.0
	v_mul_f32_e32 v84, 0x3e800000, v77
	v_fma_f32 v83, v84, v83, 1.0
	v_mul_f32_e32 v84, 0x3eaaaaab, v77
	v_fma_f32 v83, v84, v83, 1.0
	v_mul_f32_e32 v84, 0x3fb8aa3b, v77
	v_exp_f32_e32 v84, v84
	v_fma_f32 v83, v85, v83, 1.0
	v_sqrt_f32_e32 v76, v76
	v_mul_f32_e64 v83, v83, -v77
	v_sub_f32_e32 v84, 1.0, v84
	v_cmp_lt_f32_e32 vcc, -0.5, v77
	v_mul_f32_e32 v76, v80, v76
	v_cvt_pk_bf16_f32 v72, v72, v76
	v_mul_f32_e32 v76, v82, v81
	v_cndmask_b32_e32 v77, v84, v83, vcc
	v_sqrt_f32_e32 v77, v77
	v_add_f32_e32 v64, v64, v108
	v_mul_f32_e32 v64, 0xbfb8aa3b, v64
	v_add_f32_e32 v68, v68, v112
	v_mul_f32_e32 v76, v76, v77
	v_cvt_pk_bf16_f32 v73, v73, v76
	v_add_f32_e32 v76, v78, v114
	v_mul_f32_e32 v76, 0xbfb8aa3b, v76
	v_exp_f32_e32 v76, v76
	v_rcp_f32_e32 v77, v74
	v_lshlrev_b32_e32 v78, 16, v177
	v_exp_f32_e32 v64, v64
	v_add_f32_e32 v74, 1.0, v76
	v_add_f32_e32 v76, v79, v115
	v_mul_f32_e32 v76, 0xbfb8aa3b, v76
	v_exp_f32_e32 v76, v76
	v_mul_f32_e32 v78, v77, v78
	v_exp_f32_e32 v77, v75
	v_rcp_f32_e32 v74, v74
	v_add_f32_e32 v75, 1.0, v76
	v_rcp_f32_e32 v75, v75
	v_add_f32_e32 v76, 1.0, v77
	v_rcp_f32_e32 v80, v76
	v_and_b32_e32 v79, 0xffff0000, v177
	v_pk_mul_f32 v[74:75], v[74:75], s[22:23] op_sel_hi:[1,0]
	v_mul_f32_e32 v68, 0xbfb8aa3b, v68
	v_pk_mul_f32 v[74:75], v[106:107], v[74:75]
	v_exp_f32_e32 v68, v68
	v_pk_add_f32 v[76:77], v[74:75], v[74:75]
	v_add_f32_e32 v64, 1.0, v64
	v_fma_f32 v81, v76, s66, 1.0
	v_mul_f32_e32 v82, 0x3e4ccccd, v76
	v_fma_f32 v81, v82, v81, 1.0
	v_mul_f32_e32 v82, 0x3e800000, v76
	v_fma_f32 v81, v82, v81, 1.0
	v_mul_f32_e32 v82, 0x3eaaaaab, v76
	v_fma_f32 v81, v82, v81, 1.0
	v_mul_f32_e32 v82, 0x3fb8aa3b, v76
	v_exp_f32_e32 v82, v82
	v_mul_f32_e32 v83, 0.5, v76
	v_fma_f32 v81, v83, v81, 1.0
	v_mul_f32_e64 v81, v81, -v76
	v_sub_f32_e32 v82, 1.0, v82
	v_cmp_lt_f32_e32 vcc, -0.5, v76
	v_mul_f32_e32 v83, 0.5, v77
	v_add_f32_e32 v65, v65, v109
	v_cndmask_b32_e32 v76, v82, v81, vcc
	v_fma_f32 v81, v77, s66, 1.0
	v_mul_f32_e32 v82, 0x3e4ccccd, v77
	v_fma_f32 v81, v82, v81, 1.0
	v_mul_f32_e32 v82, 0x3e800000, v77
	v_fma_f32 v81, v82, v81, 1.0
	v_mul_f32_e32 v82, 0x3eaaaaab, v77
	v_fma_f32 v81, v82, v81, 1.0
	v_mul_f32_e32 v82, 0x3fb8aa3b, v77
	v_exp_f32_e32 v82, v82
	v_fma_f32 v81, v83, v81, 1.0
	v_sqrt_f32_e32 v76, v76
	v_mul_f32_e64 v81, v81, -v77
	v_sub_f32_e32 v82, 1.0, v82
	v_cmp_lt_f32_e32 vcc, -0.5, v77
	v_mul_f32_e32 v76, v78, v76
	v_cvt_pk_bf16_f32 v74, v74, v76
	v_mul_f32_e32 v76, v80, v79
	v_cndmask_b32_e32 v77, v82, v81, vcc
	v_sqrt_f32_e32 v77, v77
	v_mul_f32_e32 v65, 0xbfb8aa3b, v65
	v_add_f32_e32 v66, v66, v110
	v_mul_f32_e32 v66, 0xbfb8aa3b, v66
	v_mul_f32_e32 v76, v76, v77
	v_cvt_pk_bf16_f32 v75, v75, v76
	v_add_u32_e32 v76, 0x50000, v148
	v_mov_b32_e32 v77, v149
	v_lshl_add_u64 v[76:77], v[76:77], 2, s[72:73]
	global_store_dwordx4 v[76:77], v[72:75], off
	v_exp_f32_e32 v66, v66
	v_add_f32_e32 v67, v67, v111
	v_rcp_f32_e32 v72, v64
	v_add_f32_e32 v64, 1.0, v68
	v_add_f32_e32 v68, v69, v113
	v_mul_f32_e32 v68, 0xbfb8aa3b, v68
	v_exp_f32_e32 v68, v68
	v_exp_f32_e32 v69, v65
	v_rcp_f32_e32 v64, v64
	v_lshlrev_b32_e32 v73, 16, v174
	v_add_f32_e32 v65, 1.0, v68
	v_rcp_f32_e32 v65, v65
	v_add_f32_e32 v68, 1.0, v69
	v_rcp_f32_e32 v74, v68
	v_mul_f32_e32 v72, v72, v73
	v_pk_mul_f32 v[64:65], v[64:65], s[22:23] op_sel_hi:[1,0]
	v_and_b32_e32 v73, 0xffff0000, v174
	v_pk_mul_f32 v[64:65], v[104:105], v[64:65]
	v_add_f32_e32 v66, 1.0, v66
	v_pk_add_f32 v[68:69], v[64:65], v[64:65]
	v_mul_f32_e32 v67, 0xbfb8aa3b, v67
	v_fma_f32 v75, v68, s66, 1.0
	v_mul_f32_e32 v76, 0x3e4ccccd, v68
	v_fma_f32 v75, v76, v75, 1.0
	v_mul_f32_e32 v76, 0x3e800000, v68
	v_fma_f32 v75, v76, v75, 1.0
	v_mul_f32_e32 v76, 0x3eaaaaab, v68
	v_fma_f32 v75, v76, v75, 1.0
	v_mul_f32_e32 v76, 0x3fb8aa3b, v68
	v_exp_f32_e32 v76, v76
	v_mul_f32_e32 v77, 0.5, v68
	v_fma_f32 v75, v77, v75, 1.0
	v_mul_f32_e64 v75, v75, -v68
	v_sub_f32_e32 v76, 1.0, v76
	v_cmp_lt_f32_e32 vcc, -0.5, v68
	v_mul_f32_e32 v77, 0.5, v69
	v_add_u32_e32 v92, 16, v148
	v_cndmask_b32_e32 v68, v76, v75, vcc
	v_fma_f32 v75, v69, s66, 1.0
	v_mul_f32_e32 v76, 0x3e4ccccd, v69
	v_fma_f32 v75, v76, v75, 1.0
	v_mul_f32_e32 v76, 0x3e800000, v69
	v_fma_f32 v75, v76, v75, 1.0
	v_mul_f32_e32 v76, 0x3eaaaaab, v69
	v_fma_f32 v75, v76, v75, 1.0
	v_mul_f32_e32 v76, 0x3fb8aa3b, v69
	v_exp_f32_e32 v76, v76
	v_fma_f32 v75, v77, v75, 1.0
	v_sqrt_f32_e32 v68, v68
	v_mul_f32_e64 v75, v75, -v69
	v_sub_f32_e32 v76, 1.0, v76
	v_cmp_lt_f32_e32 vcc, -0.5, v69
	v_mul_f32_e32 v68, v72, v68
	v_cvt_pk_bf16_f32 v64, v64, v68
	v_mul_f32_e32 v68, v74, v73
	v_cndmask_b32_e32 v69, v76, v75, vcc
	v_sqrt_f32_e32 v69, v69
	s_nop 0
	v_mul_f32_e32 v68, v68, v69
	v_cvt_pk_bf16_f32 v65, v65, v68
	v_add_f32_e32 v68, v70, v114
	v_mul_f32_e32 v68, 0xbfb8aa3b, v68
	v_exp_f32_e32 v68, v68
	v_rcp_f32_e32 v69, v66
	v_lshlrev_b32_e32 v70, 16, v175
	v_add_f32_e32 v66, 1.0, v68
	v_add_f32_e32 v68, v71, v115
	v_mul_f32_e32 v68, 0xbfb8aa3b, v68
	v_exp_f32_e32 v68, v68
	v_mul_f32_e32 v70, v69, v70
	v_exp_f32_e32 v69, v67
	v_rcp_f32_e32 v66, v66
	v_add_f32_e32 v67, 1.0, v68
	v_rcp_f32_e32 v67, v67
	v_add_f32_e32 v68, 1.0, v69
	v_rcp_f32_e32 v72, v68
	v_and_b32_e32 v71, 0xffff0000, v175
	v_pk_mul_f32 v[66:67], v[66:67], s[22:23] op_sel_hi:[1,0]
	s_nop 0
	v_pk_mul_f32 v[66:67], v[106:107], v[66:67]
	s_nop 0
	v_pk_add_f32 v[68:69], v[66:67], v[66:67]
	s_nop 0
	v_fma_f32 v73, v68, s66, 1.0
	v_mul_f32_e32 v74, 0x3e4ccccd, v68
	v_fma_f32 v73, v74, v73, 1.0
	v_mul_f32_e32 v74, 0x3e800000, v68
	v_fma_f32 v73, v74, v73, 1.0
	v_mul_f32_e32 v74, 0x3eaaaaab, v68
	v_fma_f32 v73, v74, v73, 1.0
	v_mul_f32_e32 v74, 0x3fb8aa3b, v68
	v_exp_f32_e32 v74, v74
	v_mul_f32_e32 v75, 0.5, v68
	v_fma_f32 v73, v75, v73, 1.0
	v_mul_f32_e64 v73, v73, -v68
	v_sub_f32_e32 v74, 1.0, v74
	v_cmp_lt_f32_e32 vcc, -0.5, v68
	v_mul_f32_e32 v75, 0.5, v69
	s_nop 0
	v_cndmask_b32_e32 v68, v74, v73, vcc
	v_fma_f32 v73, v69, s66, 1.0
	v_mul_f32_e32 v74, 0x3e4ccccd, v69
	v_fma_f32 v73, v74, v73, 1.0
	v_mul_f32_e32 v74, 0x3e800000, v69
	v_fma_f32 v73, v74, v73, 1.0
	v_mul_f32_e32 v74, 0x3eaaaaab, v69
	v_fma_f32 v73, v74, v73, 1.0
	v_mul_f32_e32 v74, 0x3fb8aa3b, v69
	v_exp_f32_e32 v74, v74
	v_fma_f32 v73, v75, v73, 1.0
	v_sqrt_f32_e32 v68, v68
	v_mul_f32_e64 v73, v73, -v69
	v_sub_f32_e32 v74, 1.0, v74
	v_cmp_lt_f32_e32 vcc, -0.5, v69
	v_mul_f32_e32 v68, v70, v68
	v_cvt_pk_bf16_f32 v66, v66, v68
	v_mul_f32_e32 v68, v72, v71
	v_cndmask_b32_e32 v69, v74, v73, vcc
	v_sqrt_f32_e32 v69, v69
	s_nop 0
	v_mul_f32_e32 v68, v68, v69
	v_cvt_pk_bf16_f32 v67, v67, v68
	v_add_u32_e32 v68, 0x58000, v148
	v_mov_b32_e32 v69, v149
	v_lshl_add_u64 v[68:69], v[68:69], 2, s[72:73]
	global_store_dwordx4 v[68:69], v[64:67], off
	s_waitcnt vmcnt(8)
	v_add_f32_e32 v56, v56, v228
	v_mul_f32_e32 v56, 0xbfb8aa3b, v56
	v_add_f32_e32 v60, v60, v232
	v_exp_f32_e32 v56, v56
	v_mul_f32_e32 v60, 0xbfb8aa3b, v60
	v_exp_f32_e32 v60, v60
	v_add_f32_e32 v57, v57, v229
	v_add_f32_e32 v56, 1.0, v56
	v_rcp_f32_e32 v93, v56
	v_add_f32_e32 v56, 1.0, v60
	v_add_f32_e32 v60, v61, v233
	v_mul_f32_e32 v60, 0xbfb8aa3b, v60
	v_exp_f32_e32 v60, v60
	v_mul_f32_e32 v57, 0xbfb8aa3b, v57
	v_exp_f32_e32 v61, v57
	v_rcp_f32_e32 v56, v56
	v_add_f32_e32 v57, 1.0, v60
	v_rcp_f32_e32 v57, v57
	v_lshlrev_b32_e32 v94, 16, v250
	v_add_f32_e32 v60, 1.0, v61
	v_mul_f32_e32 v93, v93, v94
	v_pk_mul_f32 v[56:57], v[56:57], s[22:23] op_sel_hi:[1,0]
	v_rcp_f32_e32 v94, v60
	v_pk_mul_f32 v[56:57], v[224:225], v[56:57]
	v_and_b32_e32 v250, 0xffff0000, v250
	v_pk_add_f32 v[60:61], v[56:57], v[56:57]
	v_add_f32_e32 v58, v58, v230
	v_fma_f32 v95, v60, s66, 1.0
	v_mul_f32_e32 v96, 0x3e4ccccd, v60
	v_fma_f32 v95, v96, v95, 1.0
	v_mul_f32_e32 v96, 0x3e800000, v60
	v_fma_f32 v95, v96, v95, 1.0
	v_mul_f32_e32 v96, 0x3eaaaaab, v60
	v_fma_f32 v95, v96, v95, 1.0
	v_mul_f32_e32 v96, 0x3fb8aa3b, v60
	v_exp_f32_e32 v96, v96
	v_mul_f32_e32 v97, 0.5, v60
	v_fma_f32 v95, v97, v95, 1.0
	v_mul_f32_e64 v95, v95, -v60
	v_sub_f32_e32 v96, 1.0, v96
	v_cmp_lt_f32_e32 vcc, -0.5, v60
	v_mul_f32_e32 v97, 0.5, v61
	v_mul_f32_e32 v58, 0xbfb8aa3b, v58
	v_cndmask_b32_e32 v60, v96, v95, vcc
	v_fma_f32 v95, v61, s66, 1.0
	v_mul_f32_e32 v96, 0x3e4ccccd, v61
	v_fma_f32 v95, v96, v95, 1.0
	v_mul_f32_e32 v96, 0x3e800000, v61
	v_fma_f32 v95, v96, v95, 1.0
	v_mul_f32_e32 v96, 0x3eaaaaab, v61
	v_fma_f32 v95, v96, v95, 1.0
	v_mul_f32_e32 v96, 0x3fb8aa3b, v61
	v_exp_f32_e32 v96, v96
	v_fma_f32 v95, v97, v95, 1.0
	v_sqrt_f32_e32 v60, v60
	v_mul_f32_e64 v95, v95, -v61
	v_sub_f32_e32 v96, 1.0, v96
	v_cmp_lt_f32_e32 vcc, -0.5, v61
	v_mul_f32_e32 v60, v93, v60
	v_cvt_pk_bf16_f32 v56, v56, v60
	v_mul_f32_e32 v60, v94, v250
	v_cndmask_b32_e32 v61, v96, v95, vcc
	v_sqrt_f32_e32 v61, v61
	v_exp_f32_e32 v58, v58
	v_add_f32_e32 v59, v59, v231
	v_mul_f32_e32 v59, 0xbfb8aa3b, v59
	v_mul_f32_e32 v60, v60, v61
	v_cvt_pk_bf16_f32 v57, v57, v60
	v_add_f32_e32 v60, v62, v234
	v_mul_f32_e32 v60, 0xbfb8aa3b, v60
	v_exp_f32_e32 v60, v60
	v_add_f32_e32 v58, 1.0, v58
	v_rcp_f32_e32 v61, v58
	v_lshlrev_b32_e32 v62, 16, v251
	v_add_f32_e32 v58, 1.0, v60
	v_add_f32_e32 v60, v63, v235
	v_mul_f32_e32 v60, 0xbfb8aa3b, v60
	v_exp_f32_e32 v60, v60
	v_mul_f32_e32 v62, v61, v62
	v_exp_f32_e32 v61, v59
	v_rcp_f32_e32 v58, v58
	v_add_f32_e32 v59, 1.0, v60
	v_rcp_f32_e32 v59, v59
	v_add_f32_e32 v60, 1.0, v61
	v_rcp_f32_e32 v250, v60
	v_and_b32_e32 v63, 0xffff0000, v251
	v_pk_mul_f32 v[58:59], v[58:59], s[22:23] op_sel_hi:[1,0]
	v_add_f32_e32 v48, v48, v228
	v_pk_mul_f32 v[58:59], v[226:227], v[58:59]
	v_mul_f32_e32 v48, 0xbfb8aa3b, v48
	v_pk_add_f32 v[60:61], v[58:59], v[58:59]
	v_add_f32_e32 v52, v52, v232
	v_fma_f32 v251, v60, s66, 1.0
	v_mul_f32_e32 v93, 0x3e4ccccd, v60
	v_fma_f32 v251, v93, v251, 1.0
	v_mul_f32_e32 v93, 0x3e800000, v60
	v_fma_f32 v251, v93, v251, 1.0
	v_mul_f32_e32 v93, 0x3eaaaaab, v60
	v_fma_f32 v251, v93, v251, 1.0
	v_mul_f32_e32 v93, 0x3fb8aa3b, v60
	v_exp_f32_e32 v93, v93
	v_mul_f32_e32 v94, 0.5, v60
	v_fma_f32 v251, v94, v251, 1.0
	v_mul_f32_e64 v251, v251, -v60
	v_sub_f32_e32 v93, 1.0, v93
	v_cmp_lt_f32_e32 vcc, -0.5, v60
	v_mul_f32_e32 v94, 0.5, v61
	v_exp_f32_e32 v48, v48
	v_cndmask_b32_e32 v60, v93, v251, vcc
	v_fma_f32 v251, v61, s66, 1.0
	v_mul_f32_e32 v93, 0x3e4ccccd, v61
	v_fma_f32 v251, v93, v251, 1.0
	v_mul_f32_e32 v93, 0x3e800000, v61
	v_fma_f32 v251, v93, v251, 1.0
	v_mul_f32_e32 v93, 0x3eaaaaab, v61
	v_fma_f32 v251, v93, v251, 1.0
	v_mul_f32_e32 v93, 0x3fb8aa3b, v61
	v_exp_f32_e32 v93, v93
	v_fma_f32 v251, v94, v251, 1.0
	v_sqrt_f32_e32 v60, v60
	v_mul_f32_e64 v251, v251, -v61
	v_sub_f32_e32 v93, 1.0, v93
	v_cmp_lt_f32_e32 vcc, -0.5, v61
	v_mul_f32_e32 v52, 0xbfb8aa3b, v52
	v_mul_f32_e32 v60, v62, v60
	v_cndmask_b32_e32 v61, v93, v251, vcc
	v_sqrt_f32_e32 v61, v61
	v_exp_f32_e32 v52, v52
	v_cvt_pk_bf16_f32 v58, v58, v60
	v_mul_f32_e32 v60, v250, v63
	v_mul_f32_e32 v60, v60, v61
	v_mov_b32_e32 v93, v149
	v_cvt_pk_bf16_f32 v59, v59, v60
	v_lshl_add_u64 v[60:61], v[92:93], 2, s[72:73]
	v_add_f32_e32 v48, 1.0, v48
	global_store_dwordx4 v[60:61], v[56:59], off
	v_add_f32_e32 v49, v49, v229
	v_mul_f32_e32 v49, 0xbfb8aa3b, v49
	v_rcp_f32_e32 v56, v48
	v_add_f32_e32 v48, 1.0, v52
	v_add_f32_e32 v52, v53, v233
	v_mul_f32_e32 v52, 0xbfb8aa3b, v52
	v_exp_f32_e32 v52, v52
	v_exp_f32_e32 v53, v49
	v_rcp_f32_e32 v48, v48
	v_lshlrev_b32_e32 v57, 16, v248
	v_add_f32_e32 v49, 1.0, v52
	v_rcp_f32_e32 v49, v49
	v_add_f32_e32 v52, 1.0, v53
	v_rcp_f32_e32 v58, v52
	v_mul_f32_e32 v56, v56, v57
	v_pk_mul_f32 v[48:49], v[48:49], s[22:23] op_sel_hi:[1,0]
	v_and_b32_e32 v57, 0xffff0000, v248
	v_pk_mul_f32 v[48:49], v[224:225], v[48:49]
	v_add_f32_e32 v50, v50, v230
	v_pk_add_f32 v[52:53], v[48:49], v[48:49]
	v_mul_f32_e32 v50, 0xbfb8aa3b, v50
	v_fma_f32 v59, v52, s66, 1.0
	v_mul_f32_e32 v60, 0x3e4ccccd, v52
	v_fma_f32 v59, v60, v59, 1.0
	v_mul_f32_e32 v60, 0x3e800000, v52
	v_fma_f32 v59, v60, v59, 1.0
	v_mul_f32_e32 v60, 0x3eaaaaab, v52
	v_fma_f32 v59, v60, v59, 1.0
	v_mul_f32_e32 v60, 0x3fb8aa3b, v52
	v_exp_f32_e32 v60, v60
	v_mul_f32_e32 v61, 0.5, v52
	v_fma_f32 v59, v61, v59, 1.0
	v_mul_f32_e64 v59, v59, -v52
	v_sub_f32_e32 v60, 1.0, v60
	v_cmp_lt_f32_e32 vcc, -0.5, v52
	v_mul_f32_e32 v61, 0.5, v53
	v_exp_f32_e32 v50, v50
	v_cndmask_b32_e32 v52, v60, v59, vcc
	v_fma_f32 v59, v53, s66, 1.0
	v_mul_f32_e32 v60, 0x3e4ccccd, v53
	v_fma_f32 v59, v60, v59, 1.0
	v_mul_f32_e32 v60, 0x3e800000, v53
	v_fma_f32 v59, v60, v59, 1.0
	v_mul_f32_e32 v60, 0x3eaaaaab, v53
	v_fma_f32 v59, v60, v59, 1.0
	v_mul_f32_e32 v60, 0x3fb8aa3b, v53
	v_exp_f32_e32 v60, v60
	v_fma_f32 v59, v61, v59, 1.0
	v_sqrt_f32_e32 v52, v52
	v_mul_f32_e64 v59, v59, -v53
	v_sub_f32_e32 v60, 1.0, v60
	v_cmp_lt_f32_e32 vcc, -0.5, v53
	v_mul_f32_e32 v52, v56, v52
	v_cvt_pk_bf16_f32 v48, v48, v52
	v_mul_f32_e32 v52, v58, v57
	v_cndmask_b32_e32 v53, v60, v59, vcc
	v_sqrt_f32_e32 v53, v53
	v_add_f32_e32 v50, 1.0, v50
	v_add_f32_e32 v51, v51, v231
	v_mul_f32_e32 v51, 0xbfb8aa3b, v51
	v_mul_f32_e32 v52, v52, v53
	v_cvt_pk_bf16_f32 v49, v49, v52
	v_add_f32_e32 v52, v54, v234
	v_mul_f32_e32 v52, 0xbfb8aa3b, v52
	v_exp_f32_e32 v52, v52
	v_rcp_f32_e32 v53, v50
	v_lshlrev_b32_e32 v54, 16, v249
	v_add_f32_e32 v40, v40, v228
	v_add_f32_e32 v50, 1.0, v52
	v_add_f32_e32 v52, v55, v235
	v_mul_f32_e32 v52, 0xbfb8aa3b, v52
	v_exp_f32_e32 v52, v52
	v_mul_f32_e32 v54, v53, v54
	v_exp_f32_e32 v53, v51
	v_rcp_f32_e32 v50, v50
	v_add_f32_e32 v51, 1.0, v52
	v_rcp_f32_e32 v51, v51
	v_add_f32_e32 v52, 1.0, v53
	v_rcp_f32_e32 v56, v52
	v_mul_f32_e32 v40, 0xbfb8aa3b, v40
	v_pk_mul_f32 v[50:51], v[50:51], s[22:23] op_sel_hi:[1,0]
	v_add_f32_e32 v44, v44, v232
	v_pk_mul_f32 v[50:51], v[226:227], v[50:51]
	v_and_b32_e32 v55, 0xffff0000, v249
	v_pk_add_f32 v[52:53], v[50:51], v[50:51]
	v_exp_f32_e32 v40, v40
	v_fma_f32 v57, v52, s66, 1.0
	v_mul_f32_e32 v58, 0x3e4ccccd, v52
	v_fma_f32 v57, v58, v57, 1.0
	v_mul_f32_e32 v58, 0x3e800000, v52
	v_fma_f32 v57, v58, v57, 1.0
	v_mul_f32_e32 v58, 0x3eaaaaab, v52
	v_fma_f32 v57, v58, v57, 1.0
	v_mul_f32_e32 v58, 0x3fb8aa3b, v52
	v_exp_f32_e32 v58, v58
	v_mul_f32_e32 v59, 0.5, v52
	v_fma_f32 v57, v59, v57, 1.0
	v_mul_f32_e64 v57, v57, -v52
	v_sub_f32_e32 v58, 1.0, v58
	v_cmp_lt_f32_e32 vcc, -0.5, v52
	v_mul_f32_e32 v59, 0.5, v53
	v_mul_f32_e32 v44, 0xbfb8aa3b, v44
	v_cndmask_b32_e32 v52, v58, v57, vcc
	v_fma_f32 v57, v53, s66, 1.0
	v_mul_f32_e32 v58, 0x3e4ccccd, v53
	v_fma_f32 v57, v58, v57, 1.0
	v_mul_f32_e32 v58, 0x3e800000, v53
	v_fma_f32 v57, v58, v57, 1.0
	v_mul_f32_e32 v58, 0x3eaaaaab, v53
	v_fma_f32 v57, v58, v57, 1.0
	v_mul_f32_e32 v58, 0x3fb8aa3b, v53
	v_exp_f32_e32 v58, v58
	v_fma_f32 v57, v59, v57, 1.0
	v_sqrt_f32_e32 v52, v52
	v_mul_f32_e64 v57, v57, -v53
	v_sub_f32_e32 v58, 1.0, v58
	v_cmp_lt_f32_e32 vcc, -0.5, v53
	v_mul_f32_e32 v52, v54, v52
	v_cvt_pk_bf16_f32 v50, v50, v52
	v_mul_f32_e32 v52, v56, v55
	v_cndmask_b32_e32 v53, v58, v57, vcc
	v_sqrt_f32_e32 v53, v53
	v_exp_f32_e32 v44, v44
	v_add_f32_e32 v40, 1.0, v40
	v_add_f32_e32 v41, v41, v229
	v_mul_f32_e32 v52, v52, v53
	v_cvt_pk_bf16_f32 v51, v51, v52
	v_add_u32_e32 v52, 0x8010, v148
	v_mov_b32_e32 v53, v149
	v_lshl_add_u64 v[52:53], v[52:53], 2, s[72:73]
	global_store_dwordx4 v[52:53], v[48:51], off
	v_mul_f32_e32 v41, 0xbfb8aa3b, v41
	v_add_f32_e32 v42, v42, v230
	v_rcp_f32_e32 v48, v40
	v_add_f32_e32 v40, 1.0, v44
	v_add_f32_e32 v44, v45, v233
	v_mul_f32_e32 v44, 0xbfb8aa3b, v44
	v_exp_f32_e32 v44, v44
	v_exp_f32_e32 v45, v41
	v_rcp_f32_e32 v40, v40
	v_lshlrev_b32_e32 v49, 16, v246
	v_add_f32_e32 v41, 1.0, v44
	v_rcp_f32_e32 v41, v41
	v_add_f32_e32 v44, 1.0, v45
	v_rcp_f32_e32 v50, v44
	v_mul_f32_e32 v48, v48, v49
	v_pk_mul_f32 v[40:41], v[40:41], s[22:23] op_sel_hi:[1,0]
	v_and_b32_e32 v49, 0xffff0000, v246
	v_pk_mul_f32 v[40:41], v[224:225], v[40:41]
	v_mul_f32_e32 v42, 0xbfb8aa3b, v42
	v_pk_add_f32 v[44:45], v[40:41], v[40:41]
	v_exp_f32_e32 v42, v42
	v_fma_f32 v51, v44, s66, 1.0
	v_mul_f32_e32 v52, 0x3e4ccccd, v44
	v_fma_f32 v51, v52, v51, 1.0
	v_mul_f32_e32 v52, 0x3e800000, v44
	v_fma_f32 v51, v52, v51, 1.0
	v_mul_f32_e32 v52, 0x3eaaaaab, v44
	v_fma_f32 v51, v52, v51, 1.0
	v_mul_f32_e32 v52, 0x3fb8aa3b, v44
	v_exp_f32_e32 v52, v52
	v_mul_f32_e32 v53, 0.5, v44
	v_fma_f32 v51, v53, v51, 1.0
	v_mul_f32_e64 v51, v51, -v44
	v_sub_f32_e32 v52, 1.0, v52
	v_cmp_lt_f32_e32 vcc, -0.5, v44
	v_mul_f32_e32 v53, 0.5, v45
	v_add_f32_e32 v42, 1.0, v42
	v_cndmask_b32_e32 v44, v52, v51, vcc
	v_fma_f32 v51, v45, s66, 1.0
	v_mul_f32_e32 v52, 0x3e4ccccd, v45
	v_fma_f32 v51, v52, v51, 1.0
	v_mul_f32_e32 v52, 0x3e800000, v45
	v_fma_f32 v51, v52, v51, 1.0
	v_mul_f32_e32 v52, 0x3eaaaaab, v45
	v_fma_f32 v51, v52, v51, 1.0
	v_mul_f32_e32 v52, 0x3fb8aa3b, v45
	v_exp_f32_e32 v52, v52
	v_fma_f32 v51, v53, v51, 1.0
	v_sqrt_f32_e32 v44, v44
	v_mul_f32_e64 v51, v51, -v45
	v_sub_f32_e32 v52, 1.0, v52
	v_cmp_lt_f32_e32 vcc, -0.5, v45
	v_mul_f32_e32 v44, v48, v44
	v_cvt_pk_bf16_f32 v40, v40, v44
	v_mul_f32_e32 v44, v50, v49
	v_cndmask_b32_e32 v45, v52, v51, vcc
	v_sqrt_f32_e32 v45, v45
	v_add_f32_e32 v43, v43, v231
	v_mul_f32_e32 v43, 0xbfb8aa3b, v43
	v_add_f32_e32 v32, v32, v228
	v_mul_f32_e32 v44, v44, v45
	v_cvt_pk_bf16_f32 v41, v41, v44
	v_add_f32_e32 v44, v46, v234
	v_mul_f32_e32 v44, 0xbfb8aa3b, v44
	v_exp_f32_e32 v44, v44
	v_rcp_f32_e32 v45, v42
	v_lshlrev_b32_e32 v46, 16, v247
	v_mul_f32_e32 v32, 0xbfb8aa3b, v32
	v_add_f32_e32 v42, 1.0, v44
	v_add_f32_e32 v44, v47, v235
	v_mul_f32_e32 v44, 0xbfb8aa3b, v44
	v_exp_f32_e32 v44, v44
	v_mul_f32_e32 v46, v45, v46
	v_exp_f32_e32 v45, v43
	v_rcp_f32_e32 v42, v42
	v_add_f32_e32 v43, 1.0, v44
	v_rcp_f32_e32 v43, v43
	v_add_f32_e32 v44, 1.0, v45
	v_rcp_f32_e32 v48, v44
	v_add_f32_e32 v36, v36, v232
	v_pk_mul_f32 v[42:43], v[42:43], s[22:23] op_sel_hi:[1,0]
	v_and_b32_e32 v47, 0xffff0000, v247
	v_pk_mul_f32 v[42:43], v[226:227], v[42:43]
	v_exp_f32_e32 v32, v32
	v_pk_add_f32 v[44:45], v[42:43], v[42:43]
	v_mul_f32_e32 v36, 0xbfb8aa3b, v36
	v_fma_f32 v49, v44, s66, 1.0
	v_mul_f32_e32 v50, 0x3e4ccccd, v44
	v_fma_f32 v49, v50, v49, 1.0
	v_mul_f32_e32 v50, 0x3e800000, v44
	v_fma_f32 v49, v50, v49, 1.0
	v_mul_f32_e32 v50, 0x3eaaaaab, v44
	v_fma_f32 v49, v50, v49, 1.0
	v_mul_f32_e32 v50, 0x3fb8aa3b, v44
	v_exp_f32_e32 v50, v50
	v_mul_f32_e32 v51, 0.5, v44
	v_fma_f32 v49, v51, v49, 1.0
	v_mul_f32_e64 v49, v49, -v44
	v_sub_f32_e32 v50, 1.0, v50
	v_cmp_lt_f32_e32 vcc, -0.5, v44
	v_mul_f32_e32 v51, 0.5, v45
	v_exp_f32_e32 v36, v36
	v_cndmask_b32_e32 v44, v50, v49, vcc
	v_fma_f32 v49, v45, s66, 1.0
	v_mul_f32_e32 v50, 0x3e4ccccd, v45
	v_fma_f32 v49, v50, v49, 1.0
	v_mul_f32_e32 v50, 0x3e800000, v45
	v_fma_f32 v49, v50, v49, 1.0
	v_mul_f32_e32 v50, 0x3eaaaaab, v45
	v_fma_f32 v49, v50, v49, 1.0
	v_mul_f32_e32 v50, 0x3fb8aa3b, v45
	v_exp_f32_e32 v50, v50
	v_fma_f32 v49, v51, v49, 1.0
	v_sqrt_f32_e32 v44, v44
	v_mul_f32_e64 v49, v49, -v45
	v_sub_f32_e32 v50, 1.0, v50
	v_cmp_lt_f32_e32 vcc, -0.5, v45
	v_mul_f32_e32 v44, v46, v44
	v_cvt_pk_bf16_f32 v42, v42, v44
	v_mul_f32_e32 v44, v48, v47
	v_cndmask_b32_e32 v45, v50, v49, vcc
	v_sqrt_f32_e32 v45, v45
	v_add_f32_e32 v32, 1.0, v32
	v_add_f32_e32 v33, v33, v229
	v_mul_f32_e32 v33, 0xbfb8aa3b, v33
	v_mul_f32_e32 v44, v44, v45
	v_cvt_pk_bf16_f32 v43, v43, v44
	v_add_u32_e32 v44, 0x10010, v148
	v_mov_b32_e32 v45, v149
	v_lshl_add_u64 v[44:45], v[44:45], 2, s[72:73]
	global_store_dwordx4 v[44:45], v[40:43], off
	v_add_f32_e32 v34, v34, v230
	v_mul_f32_e32 v34, 0xbfb8aa3b, v34
	v_rcp_f32_e32 v40, v32
	v_add_f32_e32 v32, 1.0, v36
	v_add_f32_e32 v36, v37, v233
	v_mul_f32_e32 v36, 0xbfb8aa3b, v36
	v_exp_f32_e32 v36, v36
	v_exp_f32_e32 v37, v33
	v_rcp_f32_e32 v32, v32
	v_lshlrev_b32_e32 v41, 16, v244
	v_add_f32_e32 v33, 1.0, v36
	v_rcp_f32_e32 v33, v33
	v_add_f32_e32 v36, 1.0, v37
	v_rcp_f32_e32 v42, v36
	v_mul_f32_e32 v40, v40, v41
	v_pk_mul_f32 v[32:33], v[32:33], s[22:23] op_sel_hi:[1,0]
	v_and_b32_e32 v41, 0xffff0000, v244
	v_pk_mul_f32 v[32:33], v[224:225], v[32:33]
	v_exp_f32_e32 v34, v34
	v_pk_add_f32 v[36:37], v[32:33], v[32:33]
	v_add_f32_e32 v35, v35, v231
	v_fma_f32 v43, v36, s66, 1.0
	v_mul_f32_e32 v44, 0x3e4ccccd, v36
	v_fma_f32 v43, v44, v43, 1.0
	v_mul_f32_e32 v44, 0x3e800000, v36
	v_fma_f32 v43, v44, v43, 1.0
	v_mul_f32_e32 v44, 0x3eaaaaab, v36
	v_fma_f32 v43, v44, v43, 1.0
	v_mul_f32_e32 v44, 0x3fb8aa3b, v36
	v_exp_f32_e32 v44, v44
	v_mul_f32_e32 v45, 0.5, v36
	v_fma_f32 v43, v45, v43, 1.0
	v_mul_f32_e64 v43, v43, -v36
	v_sub_f32_e32 v44, 1.0, v44
	v_cmp_lt_f32_e32 vcc, -0.5, v36
	v_mul_f32_e32 v45, 0.5, v37
	v_add_f32_e32 v34, 1.0, v34
	v_cndmask_b32_e32 v36, v44, v43, vcc
	v_fma_f32 v43, v37, s66, 1.0
	v_mul_f32_e32 v44, 0x3e4ccccd, v37
	v_fma_f32 v43, v44, v43, 1.0
	v_mul_f32_e32 v44, 0x3e800000, v37
	v_fma_f32 v43, v44, v43, 1.0
	v_mul_f32_e32 v44, 0x3eaaaaab, v37
	v_fma_f32 v43, v44, v43, 1.0
	v_mul_f32_e32 v44, 0x3fb8aa3b, v37
	v_exp_f32_e32 v44, v44
	v_fma_f32 v43, v45, v43, 1.0
	v_sqrt_f32_e32 v36, v36
	v_mul_f32_e64 v43, v43, -v37
	v_sub_f32_e32 v44, 1.0, v44
	v_cmp_lt_f32_e32 vcc, -0.5, v37
	v_mul_f32_e32 v36, v40, v36
	v_cvt_pk_bf16_f32 v32, v32, v36
	v_mul_f32_e32 v36, v42, v41
	v_cndmask_b32_e32 v37, v44, v43, vcc
	v_sqrt_f32_e32 v37, v37
	v_mul_f32_e32 v35, 0xbfb8aa3b, v35
	v_add_f32_e32 v24, v24, v228
	v_mul_f32_e32 v24, 0xbfb8aa3b, v24
	v_mul_f32_e32 v36, v36, v37
	v_cvt_pk_bf16_f32 v33, v33, v36
	v_add_f32_e32 v36, v38, v234
	v_mul_f32_e32 v36, 0xbfb8aa3b, v36
	v_exp_f32_e32 v36, v36
	v_rcp_f32_e32 v37, v34
	v_lshlrev_b32_e32 v38, 16, v245
	v_add_f32_e32 v28, v28, v232
	v_add_f32_e32 v34, 1.0, v36
	v_add_f32_e32 v36, v39, v235
	v_mul_f32_e32 v36, 0xbfb8aa3b, v36
	v_exp_f32_e32 v36, v36
	v_mul_f32_e32 v38, v37, v38
	v_exp_f32_e32 v37, v35
	v_rcp_f32_e32 v34, v34
	v_add_f32_e32 v35, 1.0, v36
	v_rcp_f32_e32 v35, v35
	v_add_f32_e32 v36, 1.0, v37
	v_rcp_f32_e32 v40, v36
	v_and_b32_e32 v39, 0xffff0000, v245
	v_pk_mul_f32 v[34:35], v[34:35], s[22:23] op_sel_hi:[1,0]
	v_exp_f32_e32 v24, v24
	v_pk_mul_f32 v[34:35], v[226:227], v[34:35]
	v_mul_f32_e32 v28, 0xbfb8aa3b, v28
	v_pk_add_f32 v[36:37], v[34:35], v[34:35]
	v_exp_f32_e32 v28, v28
	v_fma_f32 v41, v36, s66, 1.0
	v_mul_f32_e32 v42, 0x3e4ccccd, v36
	v_fma_f32 v41, v42, v41, 1.0
	v_mul_f32_e32 v42, 0x3e800000, v36
	v_fma_f32 v41, v42, v41, 1.0
	v_mul_f32_e32 v42, 0x3eaaaaab, v36
	v_fma_f32 v41, v42, v41, 1.0
	v_mul_f32_e32 v42, 0x3fb8aa3b, v36
	v_exp_f32_e32 v42, v42
	v_mul_f32_e32 v43, 0.5, v36
	v_fma_f32 v41, v43, v41, 1.0
	v_mul_f32_e64 v41, v41, -v36
	v_sub_f32_e32 v42, 1.0, v42
	v_cmp_lt_f32_e32 vcc, -0.5, v36
	v_mul_f32_e32 v43, 0.5, v37
	v_add_f32_e32 v24, 1.0, v24
	v_cndmask_b32_e32 v36, v42, v41, vcc
	v_fma_f32 v41, v37, s66, 1.0
	v_mul_f32_e32 v42, 0x3e4ccccd, v37
	v_fma_f32 v41, v42, v41, 1.0
	v_mul_f32_e32 v42, 0x3e800000, v37
	v_fma_f32 v41, v42, v41, 1.0
	v_mul_f32_e32 v42, 0x3eaaaaab, v37
	v_fma_f32 v41, v42, v41, 1.0
	v_mul_f32_e32 v42, 0x3fb8aa3b, v37
	v_exp_f32_e32 v42, v42
	v_fma_f32 v41, v43, v41, 1.0
	v_sqrt_f32_e32 v36, v36
	v_mul_f32_e64 v41, v41, -v37
	v_sub_f32_e32 v42, 1.0, v42
	v_cmp_lt_f32_e32 vcc, -0.5, v37
	v_mul_f32_e32 v36, v38, v36
	v_cvt_pk_bf16_f32 v34, v34, v36
	v_mul_f32_e32 v36, v40, v39
	v_cndmask_b32_e32 v37, v42, v41, vcc
	v_sqrt_f32_e32 v37, v37
	v_add_f32_e32 v25, v25, v229
	v_mul_f32_e32 v25, 0xbfb8aa3b, v25
	v_add_f32_e32 v26, v26, v230
	v_mul_f32_e32 v36, v36, v37
	v_cvt_pk_bf16_f32 v35, v35, v36
	v_add_u32_e32 v36, 0x18010, v148
	v_mov_b32_e32 v37, v149
	v_lshl_add_u64 v[36:37], v[36:37], 2, s[72:73]
	global_store_dwordx4 v[36:37], v[32:35], off
	v_mul_f32_e32 v26, 0xbfb8aa3b, v26
	v_exp_f32_e32 v26, v26
	v_rcp_f32_e32 v33, v24
	v_add_f32_e32 v24, 1.0, v28
	v_add_f32_e32 v28, v29, v233
	v_mul_f32_e32 v28, 0xbfb8aa3b, v28
	v_exp_f32_e32 v28, v28
	v_exp_f32_e32 v29, v25
	v_rcp_f32_e32 v24, v24
	v_lshlrev_b32_e32 v34, 16, v242
	v_add_f32_e32 v25, 1.0, v28
	v_rcp_f32_e32 v25, v25
	v_add_f32_e32 v28, 1.0, v29
	v_rcp_f32_e32 v35, v28
	v_mul_f32_e32 v33, v33, v34
	v_pk_mul_f32 v[24:25], v[24:25], s[22:23] op_sel_hi:[1,0]
	v_and_b32_e32 v34, 0xffff0000, v242
	v_pk_mul_f32 v[24:25], v[224:225], v[24:25]
	v_add_f32_e32 v26, 1.0, v26
	v_pk_add_f32 v[28:29], v[24:25], v[24:25]
	v_add_f32_e32 v27, v27, v231
	v_fma_f32 v36, v28, s66, 1.0
	v_mul_f32_e32 v37, 0x3e4ccccd, v28
	v_fma_f32 v36, v37, v36, 1.0
	v_mul_f32_e32 v37, 0x3e800000, v28
	v_fma_f32 v36, v37, v36, 1.0
	v_mul_f32_e32 v37, 0x3eaaaaab, v28
	v_fma_f32 v36, v37, v36, 1.0
	v_mul_f32_e32 v37, 0x3fb8aa3b, v28
	v_exp_f32_e32 v37, v37
	v_mul_f32_e32 v38, 0.5, v28
	v_fma_f32 v36, v38, v36, 1.0
	v_mul_f32_e64 v36, v36, -v28
	v_sub_f32_e32 v37, 1.0, v37
	v_cmp_lt_f32_e32 vcc, -0.5, v28
	v_mul_f32_e32 v38, 0.5, v29
	v_mul_f32_e32 v27, 0xbfb8aa3b, v27
	v_cndmask_b32_e32 v28, v37, v36, vcc
	v_fma_f32 v36, v29, s66, 1.0
	v_mul_f32_e32 v37, 0x3e4ccccd, v29
	v_fma_f32 v36, v37, v36, 1.0
	v_mul_f32_e32 v37, 0x3e800000, v29
	v_fma_f32 v36, v37, v36, 1.0
	v_mul_f32_e32 v37, 0x3eaaaaab, v29
	v_fma_f32 v36, v37, v36, 1.0
	v_mul_f32_e32 v37, 0x3fb8aa3b, v29
	v_exp_f32_e32 v37, v37
	v_fma_f32 v36, v38, v36, 1.0
	v_sqrt_f32_e32 v28, v28
	v_mul_f32_e64 v36, v36, -v29
	v_sub_f32_e32 v37, 1.0, v37
	v_cmp_lt_f32_e32 vcc, -0.5, v29
	v_mul_f32_e32 v28, v33, v28
	v_cvt_pk_bf16_f32 v24, v24, v28
	v_mul_f32_e32 v28, v35, v34
	v_cndmask_b32_e32 v29, v37, v36, vcc
	v_sqrt_f32_e32 v29, v29
	v_add_f32_e32 v16, v16, v228
	v_mul_f32_e32 v16, 0xbfb8aa3b, v16
	v_add_f32_e32 v20, v20, v232
	v_mul_f32_e32 v28, v28, v29
	v_cvt_pk_bf16_f32 v25, v25, v28
	v_add_f32_e32 v28, v30, v234
	v_mul_f32_e32 v28, 0xbfb8aa3b, v28
	v_exp_f32_e32 v28, v28
	v_rcp_f32_e32 v29, v26
	v_lshlrev_b32_e32 v30, 16, v243
	v_exp_f32_e32 v16, v16
	v_add_f32_e32 v26, 1.0, v28
	v_add_f32_e32 v28, v31, v235
	v_mul_f32_e32 v28, 0xbfb8aa3b, v28
	v_exp_f32_e32 v28, v28
	v_mul_f32_e32 v30, v29, v30
	v_exp_f32_e32 v29, v27
	v_rcp_f32_e32 v26, v26
	v_add_f32_e32 v27, 1.0, v28
	v_rcp_f32_e32 v27, v27
	v_add_f32_e32 v28, 1.0, v29
	v_rcp_f32_e32 v33, v28
	v_mul_f32_e32 v20, 0xbfb8aa3b, v20
	v_pk_mul_f32 v[26:27], v[26:27], s[22:23] op_sel_hi:[1,0]
	v_and_b32_e32 v31, 0xffff0000, v243
	v_pk_mul_f32 v[26:27], v[226:227], v[26:27]
	v_exp_f32_e32 v20, v20
	v_pk_add_f32 v[28:29], v[26:27], v[26:27]
	v_add_u32_e32 v32, 0x40010, v148
	v_fma_f32 v34, v28, s66, 1.0
	v_mul_f32_e32 v35, 0x3e4ccccd, v28
	v_fma_f32 v34, v35, v34, 1.0
	v_mul_f32_e32 v35, 0x3e800000, v28
	v_fma_f32 v34, v35, v34, 1.0
	v_mul_f32_e32 v35, 0x3eaaaaab, v28
	v_fma_f32 v34, v35, v34, 1.0
	v_mul_f32_e32 v35, 0x3fb8aa3b, v28
	v_exp_f32_e32 v35, v35
	v_mul_f32_e32 v36, 0.5, v28
	v_fma_f32 v34, v36, v34, 1.0
	v_mul_f32_e64 v34, v34, -v28
	v_sub_f32_e32 v35, 1.0, v35
	v_cmp_lt_f32_e32 vcc, -0.5, v28
	v_mul_f32_e32 v36, 0.5, v29
	v_add_f32_e32 v16, 1.0, v16
	v_cndmask_b32_e32 v28, v35, v34, vcc
	v_fma_f32 v34, v29, s66, 1.0
	v_mul_f32_e32 v35, 0x3e4ccccd, v29
	v_fma_f32 v34, v35, v34, 1.0
	v_mul_f32_e32 v35, 0x3e800000, v29
	v_fma_f32 v34, v35, v34, 1.0
	v_mul_f32_e32 v35, 0x3eaaaaab, v29
	v_fma_f32 v34, v35, v34, 1.0
	v_mul_f32_e32 v35, 0x3fb8aa3b, v29
	v_exp_f32_e32 v35, v35
	v_fma_f32 v34, v36, v34, 1.0
	v_sqrt_f32_e32 v28, v28
	v_mul_f32_e64 v34, v34, -v29
	v_sub_f32_e32 v35, 1.0, v35
	v_cmp_lt_f32_e32 vcc, -0.5, v29
	v_mul_f32_e32 v28, v30, v28
	v_cvt_pk_bf16_f32 v26, v26, v28
	v_mul_f32_e32 v28, v33, v31
	v_cndmask_b32_e32 v29, v35, v34, vcc
	v_sqrt_f32_e32 v29, v29
	v_mov_b32_e32 v33, v149
	v_add_f32_e32 v17, v17, v229
	v_mul_f32_e32 v17, 0xbfb8aa3b, v17
	v_mul_f32_e32 v28, v28, v29
	v_cvt_pk_bf16_f32 v27, v27, v28
	v_lshl_add_u64 v[28:29], v[32:33], 2, s[72:73]
	global_store_dwordx4 v[28:29], v[24:27], off
	v_add_f32_e32 v18, v18, v230
	v_mul_f32_e32 v18, 0xbfb8aa3b, v18
	v_rcp_f32_e32 v24, v16
	v_add_f32_e32 v16, 1.0, v20
	v_add_f32_e32 v20, v21, v233
	v_mul_f32_e32 v20, 0xbfb8aa3b, v20
	v_exp_f32_e32 v20, v20
	v_exp_f32_e32 v21, v17
	v_rcp_f32_e32 v16, v16
	v_lshlrev_b32_e32 v25, 16, v240
	v_add_f32_e32 v17, 1.0, v20
	v_rcp_f32_e32 v17, v17
	v_add_f32_e32 v20, 1.0, v21
	v_rcp_f32_e32 v26, v20
	v_mul_f32_e32 v24, v24, v25
	v_pk_mul_f32 v[16:17], v[16:17], s[22:23] op_sel_hi:[1,0]
	v_and_b32_e32 v25, 0xffff0000, v240
	v_pk_mul_f32 v[16:17], v[224:225], v[16:17]
	v_exp_f32_e32 v18, v18
	v_pk_add_f32 v[20:21], v[16:17], v[16:17]
	v_add_f32_e32 v19, v19, v231
	v_fma_f32 v27, v20, s66, 1.0
	v_mul_f32_e32 v28, 0x3e4ccccd, v20
	v_fma_f32 v27, v28, v27, 1.0
	v_mul_f32_e32 v28, 0x3e800000, v20
	v_fma_f32 v27, v28, v27, 1.0
	v_mul_f32_e32 v28, 0x3eaaaaab, v20
	v_fma_f32 v27, v28, v27, 1.0
	v_mul_f32_e32 v28, 0x3fb8aa3b, v20
	v_exp_f32_e32 v28, v28
	v_mul_f32_e32 v29, 0.5, v20
	v_fma_f32 v27, v29, v27, 1.0
	v_mul_f32_e64 v27, v27, -v20
	v_sub_f32_e32 v28, 1.0, v28
	v_cmp_lt_f32_e32 vcc, -0.5, v20
	v_mul_f32_e32 v29, 0.5, v21
	v_add_f32_e32 v18, 1.0, v18
	v_cndmask_b32_e32 v20, v28, v27, vcc
	v_fma_f32 v27, v21, s66, 1.0
	v_mul_f32_e32 v28, 0x3e4ccccd, v21
	v_fma_f32 v27, v28, v27, 1.0
	v_mul_f32_e32 v28, 0x3e800000, v21
	v_fma_f32 v27, v28, v27, 1.0
	v_mul_f32_e32 v28, 0x3eaaaaab, v21
	v_fma_f32 v27, v28, v27, 1.0
	v_mul_f32_e32 v28, 0x3fb8aa3b, v21
	v_exp_f32_e32 v28, v28
	v_fma_f32 v27, v29, v27, 1.0
	v_sqrt_f32_e32 v20, v20
	v_mul_f32_e64 v27, v27, -v21
	v_sub_f32_e32 v28, 1.0, v28
	v_cmp_lt_f32_e32 vcc, -0.5, v21
	v_mul_f32_e32 v20, v24, v20
	v_cvt_pk_bf16_f32 v16, v16, v20
	v_mul_f32_e32 v20, v26, v25
	v_cndmask_b32_e32 v21, v28, v27, vcc
	v_sqrt_f32_e32 v21, v21
	v_mul_f32_e32 v19, 0xbfb8aa3b, v19
	v_add_f32_e32 v8, v8, v228
	v_mul_f32_e32 v8, 0xbfb8aa3b, v8
	v_mul_f32_e32 v20, v20, v21
	v_cvt_pk_bf16_f32 v17, v17, v20
	v_add_f32_e32 v20, v22, v234
	v_mul_f32_e32 v20, 0xbfb8aa3b, v20
	v_exp_f32_e32 v20, v20
	v_rcp_f32_e32 v21, v18
	v_lshlrev_b32_e32 v22, 16, v241
	v_add_f32_e32 v12, v12, v232
	v_add_f32_e32 v18, 1.0, v20
	v_add_f32_e32 v20, v23, v235
	v_mul_f32_e32 v20, 0xbfb8aa3b, v20
	v_exp_f32_e32 v20, v20
	v_mul_f32_e32 v22, v21, v22
	v_exp_f32_e32 v21, v19
	v_rcp_f32_e32 v18, v18
	v_add_f32_e32 v19, 1.0, v20
	v_rcp_f32_e32 v19, v19
	v_add_f32_e32 v20, 1.0, v21
	v_rcp_f32_e32 v24, v20
	v_and_b32_e32 v23, 0xffff0000, v241
	v_pk_mul_f32 v[18:19], v[18:19], s[22:23] op_sel_hi:[1,0]
	v_exp_f32_e32 v8, v8
	v_pk_mul_f32 v[18:19], v[226:227], v[18:19]
	v_mul_f32_e32 v12, 0xbfb8aa3b, v12
	v_pk_add_f32 v[20:21], v[18:19], v[18:19]
	v_exp_f32_e32 v12, v12
	v_fma_f32 v25, v20, s66, 1.0
	v_mul_f32_e32 v26, 0x3e4ccccd, v20
	v_fma_f32 v25, v26, v25, 1.0
	v_mul_f32_e32 v26, 0x3e800000, v20
	v_fma_f32 v25, v26, v25, 1.0
	v_mul_f32_e32 v26, 0x3eaaaaab, v20
	v_fma_f32 v25, v26, v25, 1.0
	v_mul_f32_e32 v26, 0x3fb8aa3b, v20
	v_exp_f32_e32 v26, v26
	v_mul_f32_e32 v27, 0.5, v20
	v_fma_f32 v25, v27, v25, 1.0
	v_mul_f32_e64 v25, v25, -v20
	v_sub_f32_e32 v26, 1.0, v26
	v_cmp_lt_f32_e32 vcc, -0.5, v20
	v_mul_f32_e32 v27, 0.5, v21
	v_add_f32_e32 v8, 1.0, v8
	v_cndmask_b32_e32 v20, v26, v25, vcc
	v_fma_f32 v25, v21, s66, 1.0
	v_mul_f32_e32 v26, 0x3e4ccccd, v21
	v_fma_f32 v25, v26, v25, 1.0
	v_mul_f32_e32 v26, 0x3e800000, v21
	v_fma_f32 v25, v26, v25, 1.0
	v_mul_f32_e32 v26, 0x3eaaaaab, v21
	v_fma_f32 v25, v26, v25, 1.0
	v_mul_f32_e32 v26, 0x3fb8aa3b, v21
	v_exp_f32_e32 v26, v26
	v_fma_f32 v25, v27, v25, 1.0
	v_sqrt_f32_e32 v20, v20
	v_mul_f32_e64 v25, v25, -v21
	v_sub_f32_e32 v26, 1.0, v26
	v_cmp_lt_f32_e32 vcc, -0.5, v21
	v_mul_f32_e32 v20, v22, v20
	v_cvt_pk_bf16_f32 v18, v18, v20
	v_mul_f32_e32 v20, v24, v23
	v_cndmask_b32_e32 v21, v26, v25, vcc
	v_sqrt_f32_e32 v21, v21
	v_add_f32_e32 v9, v9, v229
	v_mul_f32_e32 v9, 0xbfb8aa3b, v9
	v_add_f32_e32 v10, v10, v230
	v_mul_f32_e32 v20, v20, v21
	v_cvt_pk_bf16_f32 v19, v19, v20
	v_add_u32_e32 v20, 0x48010, v148
	v_mov_b32_e32 v21, v149
	v_lshl_add_u64 v[20:21], v[20:21], 2, s[72:73]
	global_store_dwordx4 v[20:21], v[16:19], off
	v_mul_f32_e32 v10, 0xbfb8aa3b, v10
	v_exp_f32_e32 v10, v10
	v_rcp_f32_e32 v16, v8
	v_add_f32_e32 v8, 1.0, v12
	v_add_f32_e32 v12, v13, v233
	v_mul_f32_e32 v12, 0xbfb8aa3b, v12
	v_exp_f32_e32 v12, v12
	v_exp_f32_e32 v13, v9
	v_rcp_f32_e32 v8, v8
	v_lshlrev_b32_e32 v17, 16, v238
	v_add_f32_e32 v9, 1.0, v12
	v_rcp_f32_e32 v9, v9
	v_add_f32_e32 v12, 1.0, v13
	v_rcp_f32_e32 v18, v12
	v_mul_f32_e32 v16, v16, v17
	v_pk_mul_f32 v[8:9], v[8:9], s[22:23] op_sel_hi:[1,0]
	v_and_b32_e32 v17, 0xffff0000, v238
	v_pk_mul_f32 v[8:9], v[224:225], v[8:9]
	v_add_f32_e32 v10, 1.0, v10
	v_pk_add_f32 v[12:13], v[8:9], v[8:9]
	v_add_f32_e32 v11, v11, v231
	v_fma_f32 v19, v12, s66, 1.0
	v_mul_f32_e32 v20, 0x3e4ccccd, v12
	v_fma_f32 v19, v20, v19, 1.0
	v_mul_f32_e32 v20, 0x3e800000, v12
	v_fma_f32 v19, v20, v19, 1.0
	v_mul_f32_e32 v20, 0x3eaaaaab, v12
	v_fma_f32 v19, v20, v19, 1.0
	v_mul_f32_e32 v20, 0x3fb8aa3b, v12
	v_exp_f32_e32 v20, v20
	v_mul_f32_e32 v21, 0.5, v12
	v_fma_f32 v19, v21, v19, 1.0
	v_mul_f32_e64 v19, v19, -v12
	v_sub_f32_e32 v20, 1.0, v20
	v_cmp_lt_f32_e32 vcc, -0.5, v12
	v_mul_f32_e32 v21, 0.5, v13
	v_mul_f32_e32 v11, 0xbfb8aa3b, v11
	v_cndmask_b32_e32 v12, v20, v19, vcc
	v_fma_f32 v19, v13, s66, 1.0
	v_mul_f32_e32 v20, 0x3e4ccccd, v13
	v_fma_f32 v19, v20, v19, 1.0
	v_mul_f32_e32 v20, 0x3e800000, v13
	v_fma_f32 v19, v20, v19, 1.0
	v_mul_f32_e32 v20, 0x3eaaaaab, v13
	v_fma_f32 v19, v20, v19, 1.0
	v_mul_f32_e32 v20, 0x3fb8aa3b, v13
	v_exp_f32_e32 v20, v20
	v_fma_f32 v19, v21, v19, 1.0
	v_sqrt_f32_e32 v12, v12
	v_mul_f32_e64 v19, v19, -v13
	v_sub_f32_e32 v20, 1.0, v20
	v_cmp_lt_f32_e32 vcc, -0.5, v13
	v_mul_f32_e32 v12, v16, v12
	v_cvt_pk_bf16_f32 v8, v8, v12
	v_mul_f32_e32 v12, v18, v17
	v_cndmask_b32_e32 v13, v20, v19, vcc
	v_sqrt_f32_e32 v13, v13
	v_add_f32_e32 v0, v0, v228
	v_mul_f32_e32 v0, 0xbfb8aa3b, v0
	v_add_f32_e32 v4, v4, v232
	v_mul_f32_e32 v12, v12, v13
	v_cvt_pk_bf16_f32 v9, v9, v12
	v_add_f32_e32 v12, v14, v234
	v_mul_f32_e32 v12, 0xbfb8aa3b, v12
	v_exp_f32_e32 v12, v12
	v_rcp_f32_e32 v13, v10
	v_lshlrev_b32_e32 v14, 16, v239
	v_exp_f32_e32 v0, v0
	v_add_f32_e32 v10, 1.0, v12
	v_add_f32_e32 v12, v15, v235
	v_mul_f32_e32 v12, 0xbfb8aa3b, v12
	v_exp_f32_e32 v12, v12
	v_mul_f32_e32 v14, v13, v14
	v_exp_f32_e32 v13, v11
	v_rcp_f32_e32 v10, v10
	v_add_f32_e32 v11, 1.0, v12
	v_rcp_f32_e32 v11, v11
	v_add_f32_e32 v12, 1.0, v13
	v_rcp_f32_e32 v16, v12
	v_and_b32_e32 v15, 0xffff0000, v239
	v_pk_mul_f32 v[10:11], v[10:11], s[22:23] op_sel_hi:[1,0]
	v_mul_f32_e32 v4, 0xbfb8aa3b, v4
	v_pk_mul_f32 v[10:11], v[226:227], v[10:11]
	v_exp_f32_e32 v4, v4
	v_pk_add_f32 v[12:13], v[10:11], v[10:11]
	v_add_f32_e32 v0, 1.0, v0
	v_fma_f32 v17, v12, s66, 1.0
	v_mul_f32_e32 v18, 0x3e4ccccd, v12
	v_fma_f32 v17, v18, v17, 1.0
	v_mul_f32_e32 v18, 0x3e800000, v12
	v_fma_f32 v17, v18, v17, 1.0
	v_mul_f32_e32 v18, 0x3eaaaaab, v12
	v_fma_f32 v17, v18, v17, 1.0
	v_mul_f32_e32 v18, 0x3fb8aa3b, v12
	v_exp_f32_e32 v18, v18
	v_mul_f32_e32 v19, 0.5, v12
	v_fma_f32 v17, v19, v17, 1.0
	v_mul_f32_e64 v17, v17, -v12
	v_sub_f32_e32 v18, 1.0, v18
	v_cmp_lt_f32_e32 vcc, -0.5, v12
	v_mul_f32_e32 v19, 0.5, v13
	v_add_f32_e32 v1, v1, v229
	v_cndmask_b32_e32 v12, v18, v17, vcc
	v_fma_f32 v17, v13, s66, 1.0
	v_mul_f32_e32 v18, 0x3e4ccccd, v13
	v_fma_f32 v17, v18, v17, 1.0
	v_mul_f32_e32 v18, 0x3e800000, v13
	v_fma_f32 v17, v18, v17, 1.0
	v_mul_f32_e32 v18, 0x3eaaaaab, v13
	v_fma_f32 v17, v18, v17, 1.0
	v_mul_f32_e32 v18, 0x3fb8aa3b, v13
	v_exp_f32_e32 v18, v18
	v_fma_f32 v17, v19, v17, 1.0
	v_sqrt_f32_e32 v12, v12
	v_mul_f32_e64 v17, v17, -v13
	v_sub_f32_e32 v18, 1.0, v18
	v_cmp_lt_f32_e32 vcc, -0.5, v13
	v_mul_f32_e32 v12, v14, v12
	v_cvt_pk_bf16_f32 v10, v10, v12
	v_mul_f32_e32 v12, v16, v15
	v_cndmask_b32_e32 v13, v18, v17, vcc
	v_sqrt_f32_e32 v13, v13
	v_mul_f32_e32 v1, 0xbfb8aa3b, v1
	v_add_f32_e32 v2, v2, v230
	v_mul_f32_e32 v2, 0xbfb8aa3b, v2
	v_mul_f32_e32 v12, v12, v13
	v_cvt_pk_bf16_f32 v11, v11, v12
	v_add_u32_e32 v12, 0x50010, v148
	v_mov_b32_e32 v13, v149
	v_lshl_add_u64 v[12:13], v[12:13], 2, s[72:73]
	global_store_dwordx4 v[12:13], v[8:11], off
	v_exp_f32_e32 v2, v2
	v_add_f32_e32 v3, v3, v231
	v_rcp_f32_e32 v8, v0
	v_add_f32_e32 v0, 1.0, v4
	v_add_f32_e32 v4, v5, v233
	v_mul_f32_e32 v4, 0xbfb8aa3b, v4
	v_exp_f32_e32 v4, v4
	v_exp_f32_e32 v5, v1
	v_rcp_f32_e32 v0, v0
	v_lshlrev_b32_e32 v9, 16, v236
	v_add_f32_e32 v1, 1.0, v4
	v_rcp_f32_e32 v1, v1
	v_add_f32_e32 v4, 1.0, v5
	v_rcp_f32_e32 v10, v4
	v_mul_f32_e32 v8, v8, v9
	v_pk_mul_f32 v[0:1], v[0:1], s[22:23] op_sel_hi:[1,0]
	v_and_b32_e32 v9, 0xffff0000, v236
	v_pk_mul_f32 v[0:1], v[224:225], v[0:1]
	v_add_f32_e32 v2, 1.0, v2
	v_pk_add_f32 v[4:5], v[0:1], v[0:1]
	v_mul_f32_e32 v3, 0xbfb8aa3b, v3
	v_fma_f32 v11, v4, s66, 1.0
	v_mul_f32_e32 v12, 0x3e4ccccd, v4
	v_fma_f32 v11, v12, v11, 1.0
	v_mul_f32_e32 v12, 0x3e800000, v4
	v_fma_f32 v11, v12, v11, 1.0
	v_mul_f32_e32 v12, 0x3eaaaaab, v4
	v_fma_f32 v11, v12, v11, 1.0
	v_mul_f32_e32 v12, 0x3fb8aa3b, v4
	v_exp_f32_e32 v12, v12
	v_mul_f32_e32 v13, 0.5, v4
	v_fma_f32 v11, v13, v11, 1.0
	v_mul_f32_e64 v11, v11, -v4
	v_sub_f32_e32 v12, 1.0, v12
	v_cmp_lt_f32_e32 vcc, -0.5, v4
	v_mul_f32_e32 v13, 0.5, v5
	v_add_u32_e32 v148, 0x58010, v148
	v_cndmask_b32_e32 v4, v12, v11, vcc
	v_fma_f32 v11, v5, s66, 1.0
	v_mul_f32_e32 v12, 0x3e4ccccd, v5
	v_fma_f32 v11, v12, v11, 1.0
	v_mul_f32_e32 v12, 0x3e800000, v5
	v_fma_f32 v11, v12, v11, 1.0
	v_mul_f32_e32 v12, 0x3eaaaaab, v5
	v_fma_f32 v11, v12, v11, 1.0
	v_mul_f32_e32 v12, 0x3fb8aa3b, v5
	v_exp_f32_e32 v12, v12
	v_fma_f32 v11, v13, v11, 1.0
	v_sqrt_f32_e32 v4, v4
	v_mul_f32_e64 v11, v11, -v5
	v_sub_f32_e32 v12, 1.0, v12
	v_cmp_lt_f32_e32 vcc, -0.5, v5
	v_mul_f32_e32 v4, v8, v4
	v_cvt_pk_bf16_f32 v0, v0, v4
	v_mul_f32_e32 v4, v10, v9
	v_cndmask_b32_e32 v5, v12, v11, vcc
	v_sqrt_f32_e32 v5, v5
	s_nop 0
	v_mul_f32_e32 v4, v4, v5
	v_cvt_pk_bf16_f32 v1, v1, v4
	v_add_f32_e32 v4, v6, v234
	v_mul_f32_e32 v4, 0xbfb8aa3b, v4
	v_exp_f32_e32 v4, v4
	v_rcp_f32_e32 v5, v2
	v_lshlrev_b32_e32 v6, 16, v237
	v_add_f32_e32 v2, 1.0, v4
	v_add_f32_e32 v4, v7, v235
	v_mul_f32_e32 v4, 0xbfb8aa3b, v4
	v_exp_f32_e32 v4, v4
	v_mul_f32_e32 v6, v5, v6
	v_exp_f32_e32 v5, v3
	v_rcp_f32_e32 v2, v2
	v_add_f32_e32 v3, 1.0, v4
	v_rcp_f32_e32 v3, v3
	v_add_f32_e32 v4, 1.0, v5
	v_rcp_f32_e32 v8, v4
	v_and_b32_e32 v7, 0xffff0000, v237
	v_pk_mul_f32 v[2:3], v[2:3], s[22:23] op_sel_hi:[1,0]
	s_nop 0
	v_pk_mul_f32 v[2:3], v[226:227], v[2:3]
	s_nop 0
	v_pk_add_f32 v[4:5], v[2:3], v[2:3]
	s_nop 0
	v_fma_f32 v9, v4, s66, 1.0
	v_mul_f32_e32 v10, 0x3e4ccccd, v4
	v_fma_f32 v9, v10, v9, 1.0
	v_mul_f32_e32 v10, 0x3e800000, v4
	v_fma_f32 v9, v10, v9, 1.0
	v_mul_f32_e32 v10, 0x3eaaaaab, v4
	v_fma_f32 v9, v10, v9, 1.0
	v_mul_f32_e32 v10, 0x3fb8aa3b, v4
	v_exp_f32_e32 v10, v10
	v_mul_f32_e32 v11, 0.5, v4
	v_fma_f32 v9, v11, v9, 1.0
	v_mul_f32_e64 v9, v9, -v4
	v_sub_f32_e32 v10, 1.0, v10
	v_cmp_lt_f32_e32 vcc, -0.5, v4
	v_mul_f32_e32 v11, 0.5, v5
	s_nop 0
	v_cndmask_b32_e32 v4, v10, v9, vcc
	v_fma_f32 v9, v5, s66, 1.0
	v_mul_f32_e32 v10, 0x3e4ccccd, v5
	v_fma_f32 v9, v10, v9, 1.0
	v_mul_f32_e32 v10, 0x3e800000, v5
	v_fma_f32 v9, v10, v9, 1.0
	v_mul_f32_e32 v10, 0x3eaaaaab, v5
	v_fma_f32 v9, v10, v9, 1.0
	v_mul_f32_e32 v10, 0x3fb8aa3b, v5
	v_exp_f32_e32 v10, v10
	v_fma_f32 v9, v11, v9, 1.0
	v_sqrt_f32_e32 v4, v4
	v_mul_f32_e64 v9, v9, -v5
	v_sub_f32_e32 v10, 1.0, v10
	v_cmp_lt_f32_e32 vcc, -0.5, v5
	v_mul_f32_e32 v4, v6, v4
	v_cvt_pk_bf16_f32 v2, v2, v4
	v_mul_f32_e32 v4, v8, v7
	v_cndmask_b32_e32 v5, v10, v9, vcc
	v_sqrt_f32_e32 v5, v5
	s_and_b64 vcc, exec, s[4:5]
	s_mov_b64 s[4:5], -1
	v_mul_f32_e32 v4, v4, v5
	v_cvt_pk_bf16_f32 v3, v3, v4
	v_lshl_add_u64 v[4:5], v[148:149], 2, s[72:73]
	global_store_dwordx4 v[4:5], v[0:3], off
	s_cbranch_vccnz .LBB0_305
	s_andn2_b64 vcc, exec, s[0:1]
	s_cbranch_vccnz .LBB0_304
	s_barrier
	s_branch .LBB0_304

.LBB0_519:
	s_lshl_b32 s6, s6, 8
	v_mov_b32_e32 v120, v212
	v_mov_b32_e32 v220, v213
	s_add_i32 s6, s6, s43
	v_readlane_b32 s52, v254, 7
	v_add_u32_e32 v219, s6, v120
	s_lshl_b32 s6, s30, 8
	s_or_b32 s6, s6, s44
	v_lshl_add_u32 v204, v220, 3, s6
	v_ashrrev_i32_e32 v205, 31, v204
	v_readlane_b32 s53, v254, 8
	v_lshlrev_b32_e32 v194, 11, v219
	v_cndmask_b32_e64 v221, 0, 1, s[18:19]
	v_lshl_add_u64 v[206:207], v[204:205], 2, s[52:53]
	s_and_b64 vcc, exec, s[18:19]
	s_cbranch_vccz .Lg3_nobias
	v_lshl_add_u64 v[248:249], v[204:205], 2, s[16:17]
	global_load_dwordx4 v[232:235], v[248:249], off
	global_load_dwordx4 v[236:239], v[248:249], off offset:16
	global_load_dwordx4 v[240:243], v[248:249], off offset:512
	global_load_dwordx4 v[244:247], v[248:249], off offset:528
.Lg3_nobias:
	v_lshl_add_u64 v[120:121], v[194:195], 2, v[206:207]
	global_load_dwordx4 v[222:225], v[120:121], off offset:16
	global_load_dwordx4 v[208:211], v[120:121], off
	global_load_dwordx4 v[176:179], v[120:121], off offset:528
	global_load_dwordx4 v[180:183], v[120:121], off offset:512
	v_add_u32_e32 v120, 0x8000, v194
	v_mov_b32_e32 v121, v195
	v_lshl_add_u64 v[120:121], v[120:121], 2, v[206:207]
	global_load_dwordx4 v[168:171], v[120:121], off offset:16
	global_load_dwordx4 v[172:175], v[120:121], off
	global_load_dwordx4 v[160:163], v[120:121], off offset:528
	global_load_dwordx4 v[164:167], v[120:121], off offset:512
	v_add_u32_e32 v120, 0x10000, v194
	v_mov_b32_e32 v121, v195
	v_lshl_add_u64 v[120:121], v[120:121], 2, v[206:207]
	global_load_dwordx4 v[152:155], v[120:121], off offset:16
	global_load_dwordx4 v[156:159], v[120:121], off
	global_load_dwordx4 v[144:147], v[120:121], off offset:528
	global_load_dwordx4 v[148:151], v[120:121], off offset:512
	v_add_u32_e32 v120, 0x18000, v194
	v_mov_b32_e32 v121, v195
	v_lshl_add_u64 v[132:133], v[120:121], 2, v[206:207]
	global_load_dwordx4 v[136:139], v[132:133], off offset:16
	global_load_dwordx4 v[140:143], v[132:133], off
	global_load_dwordx4 v[120:123], v[132:133], off offset:528
	s_nop 0
	global_load_dwordx4 v[132:135], v[132:133], off offset:512
	v_cmp_ne_u32_e64 s[6:7], 1, v221
	s_andn2_b64 vcc, exec, s[18:19]
	v_readlane_b32 s54, v254, 9
	v_readlane_b32 s55, v254, 10
	v_readlane_b32 s56, v254, 11
	v_readlane_b32 s57, v254, 12
	v_readlane_b32 s58, v254, 13
	v_readlane_b32 s59, v254, 14
	v_readlane_b32 s60, v254, 15
	v_readlane_b32 s61, v254, 16
	v_readlane_b32 s62, v254, 17
	v_readlane_b32 s63, v254, 18
	v_readlane_b32 s64, v254, 19
	v_readlane_b32 s65, v254, 20
	v_readlane_b32 s66, v254, 21
	v_readlane_b32 s67, v254, 22
	s_waitcnt vmcnt(0)
	v_pk_add_f32 v[126:127], v[126:127], v[224:225]
	v_pk_add_f32 v[130:131], v[130:131], v[210:211]
	v_pk_add_f32 v[208:209], v[128:129], v[208:209]
	v_pk_add_f32 v[128:129], v[124:125], v[222:223]
	v_lshl_add_u64 v[124:125], v[204:205], 2, s[16:17]
	s_cbranch_vccnz .LBB0_521
	v_pk_add_f32 v[130:131], v[130:131], v[234:235]
	v_pk_add_f32 v[208:209], v[208:209], v[232:233]
	v_pk_add_f32 v[126:127], v[126:127], v[238:239]
	v_pk_add_f32 v[128:129], v[128:129], v[236:237]
.LBB0_521:
	v_add_u32_e32 v210, v194, v204
	v_mov_b32_e32 v211, v195
	v_lshl_add_u64 v[226:227], v[210:211], 1, s[72:73]
	v_pk_add_f32 v[118:119], v[118:119], v[182:183]
	v_pk_add_f32 v[116:117], v[116:117], v[180:181]
	v_pk_add_f32 v[114:115], v[114:115], v[178:179]
	s_and_b64 vcc, exec, s[6:7]
	v_pk_add_f32 v[112:113], v[112:113], v[176:177]
	v_cvt_pk_bf16_f32 v222, v208, v209
	v_cvt_pk_bf16_f32 v223, v130, v131
	v_cvt_pk_bf16_f32 v224, v128, v129
	v_cvt_pk_bf16_f32 v225, v126, v127
	global_store_dwordx4 v[226:227], v[222:225], off
	s_cbranch_vccnz .LBB0_523
	v_pk_add_f32 v[118:119], v[118:119], v[242:243]
	v_pk_add_f32 v[116:117], v[116:117], v[240:241]
	v_pk_add_f32 v[114:115], v[114:115], v[246:247]
	v_pk_add_f32 v[112:113], v[112:113], v[244:245]

.LBB0_525:
	s_or_b64 exec, exec, s[30:31]
	v_pk_add_f32 v[110:111], v[110:111], v[174:175]
	v_pk_add_f32 v[108:109], v[108:109], v[172:173]
	v_pk_add_f32 v[106:107], v[106:107], v[170:171]
	s_and_b64 vcc, exec, s[6:7]
	s_waitcnt lgkmcnt(0)
	v_pk_add_f32 v[112:113], v[104:105], v[168:169]
	s_cbranch_vccnz .LBB0_527
	v_pk_add_f32 v[110:111], v[110:111], v[234:235]
	v_pk_add_f32 v[108:109], v[108:109], v[232:233]
	v_pk_add_f32 v[106:107], v[106:107], v[238:239]
	v_pk_add_f32 v[112:113], v[112:113], v[236:237]
.LBB0_527:
	v_add_u32_e32 v114, 16, v219
	v_lshl_add_u32 v104, v114, 11, v204
	v_mov_b32_e32 v105, v195
	v_lshl_add_u64 v[128:129], v[104:105], 1, s[72:73]
	v_pk_add_f32 v[102:103], v[102:103], v[166:167]
	v_pk_add_f32 v[100:101], v[100:101], v[164:165]
	v_pk_add_f32 v[98:99], v[98:99], v[162:163]
	s_and_b64 vcc, exec, s[6:7]
	v_pk_add_f32 v[96:97], v[96:97], v[160:161]
	v_cvt_pk_bf16_f32 v116, v108, v109
	v_cvt_pk_bf16_f32 v117, v110, v111
	v_cvt_pk_bf16_f32 v118, v112, v113
	v_cvt_pk_bf16_f32 v119, v106, v107
	global_store_dwordx4 v[128:129], v[116:119], off
	s_cbranch_vccnz .LBB0_529
	v_pk_add_f32 v[102:103], v[102:103], v[242:243]
	v_pk_add_f32 v[100:101], v[100:101], v[240:241]
	v_pk_add_f32 v[98:99], v[98:99], v[246:247]
	v_pk_add_f32 v[96:97], v[96:97], v[244:245]

.LBB0_531:
	s_or_b64 exec, exec, s[30:31]
	v_pk_add_f32 v[94:95], v[94:95], v[158:159]
	v_pk_add_f32 v[92:93], v[92:93], v[156:157]
	v_pk_add_f32 v[90:91], v[90:91], v[154:155]
	s_and_b64 vcc, exec, s[6:7]
	s_waitcnt lgkmcnt(0)
	v_pk_add_f32 v[96:97], v[88:89], v[152:153]
	s_cbranch_vccnz .LBB0_533
	v_pk_add_f32 v[94:95], v[94:95], v[234:235]
	v_pk_add_f32 v[92:93], v[92:93], v[232:233]
	v_pk_add_f32 v[90:91], v[90:91], v[238:239]
	v_pk_add_f32 v[96:97], v[96:97], v[236:237]
.LBB0_533:
	v_add_u32_e32 v98, 32, v219
	v_lshl_add_u32 v88, v98, 11, v204
	v_mov_b32_e32 v89, v195
	v_lshl_add_u64 v[104:105], v[88:89], 1, s[72:73]
	v_pk_add_f32 v[86:87], v[86:87], v[150:151]
	v_pk_add_f32 v[84:85], v[84:85], v[148:149]
	v_pk_add_f32 v[82:83], v[82:83], v[146:147]
	s_and_b64 vcc, exec, s[6:7]
	v_pk_add_f32 v[80:81], v[80:81], v[144:145]
	v_cvt_pk_bf16_f32 v100, v92, v93
	v_cvt_pk_bf16_f32 v101, v94, v95
	v_cvt_pk_bf16_f32 v102, v96, v97
	v_cvt_pk_bf16_f32 v103, v90, v91
	global_store_dwordx4 v[104:105], v[100:103], off
	s_cbranch_vccnz .LBB0_535
	v_pk_add_f32 v[86:87], v[86:87], v[242:243]
	v_pk_add_f32 v[84:85], v[84:85], v[240:241]
	v_pk_add_f32 v[82:83], v[82:83], v[246:247]
	v_pk_add_f32 v[80:81], v[80:81], v[244:245]

.LBB0_537:
	s_or_b64 exec, exec, s[30:31]
	v_pk_add_f32 v[78:79], v[78:79], v[142:143]
	v_pk_add_f32 v[76:77], v[76:77], v[140:141]
	v_pk_add_f32 v[74:75], v[74:75], v[138:139]
	s_and_b64 vcc, exec, s[6:7]
	s_waitcnt lgkmcnt(0)
	v_pk_add_f32 v[80:81], v[72:73], v[136:137]
	s_cbranch_vccnz .LBB0_539
	v_pk_add_f32 v[78:79], v[78:79], v[234:235]
	v_pk_add_f32 v[76:77], v[76:77], v[232:233]
	v_pk_add_f32 v[74:75], v[74:75], v[238:239]
	v_pk_add_f32 v[80:81], v[80:81], v[236:237]
.LBB0_539:
	v_add_u32_e32 v82, 48, v219
	v_lshl_add_u32 v72, v82, 11, v204
	v_mov_b32_e32 v73, v195
	v_lshl_add_u64 v[88:89], v[72:73], 1, s[72:73]
	v_pk_add_f32 v[70:71], v[70:71], v[134:135]
	v_pk_add_f32 v[68:69], v[68:69], v[132:133]
	v_pk_add_f32 v[66:67], v[66:67], v[122:123]
	s_and_b64 vcc, exec, s[6:7]
	v_pk_add_f32 v[64:65], v[64:65], v[120:121]
	v_cvt_pk_bf16_f32 v84, v76, v77
	v_cvt_pk_bf16_f32 v85, v78, v79
	v_cvt_pk_bf16_f32 v86, v80, v81
	v_cvt_pk_bf16_f32 v87, v74, v75
	global_store_dwordx4 v[88:89], v[84:87], off
	s_cbranch_vccnz .LBB0_541
	v_pk_add_f32 v[70:71], v[70:71], v[242:243]
	v_pk_add_f32 v[68:69], v[68:69], v[240:241]
	v_pk_add_f32 v[66:67], v[66:67], v[246:247]
	v_pk_add_f32 v[64:65], v[64:65], v[244:245]

.LBB0_543:
	s_or_b64 exec, exec, s[30:31]
	v_add_u32_e32 v64, 0x40000, v194
	s_waitcnt lgkmcnt(0)
	v_mov_b32_e32 v65, v195
	v_lshl_add_u64 v[64:65], v[64:65], 2, v[206:207]
	global_load_dwordx4 v[120:123], v[64:65], off offset:16
	global_load_dwordx4 v[128:131], v[64:65], off
	global_load_dwordx4 v[112:115], v[64:65], off offset:528
	global_load_dwordx4 v[116:119], v[64:65], off offset:512
	v_add_u32_e32 v64, 0x48000, v194
	v_mov_b32_e32 v65, v195
	v_lshl_add_u64 v[64:65], v[64:65], 2, v[206:207]
	global_load_dwordx4 v[104:107], v[64:65], off offset:16
	global_load_dwordx4 v[108:111], v[64:65], off
	global_load_dwordx4 v[96:99], v[64:65], off offset:528
	global_load_dwordx4 v[100:103], v[64:65], off offset:512
	v_add_u32_e32 v64, 0x50000, v194
	v_mov_b32_e32 v65, v195
	v_add_u32_e32 v194, 0x58000, v194
	v_lshl_add_u64 v[64:65], v[64:65], 2, v[206:207]
	v_lshl_add_u64 v[68:69], v[194:195], 2, v[206:207]
	global_load_dwordx4 v[88:91], v[64:65], off offset:16
	global_load_dwordx4 v[92:95], v[64:65], off
	global_load_dwordx4 v[80:83], v[64:65], off offset:528
	global_load_dwordx4 v[84:87], v[64:65], off offset:512
	global_load_dwordx4 v[72:75], v[68:69], off offset:16
	global_load_dwordx4 v[76:79], v[68:69], off
	s_nop 0
	global_load_dwordx4 v[64:67], v[68:69], off offset:528
	s_nop 0
	global_load_dwordx4 v[68:71], v[68:69], off offset:512
	s_and_b64 vcc, exec, s[6:7]
	s_waitcnt vmcnt(15)
	v_pk_add_f32 v[58:59], v[58:59], v[122:123]
	s_waitcnt vmcnt(14)
	v_pk_add_f32 v[62:63], v[62:63], v[130:131]
	v_pk_add_f32 v[60:61], v[60:61], v[128:129]
	v_pk_add_f32 v[56:57], v[56:57], v[120:121]
	s_cbranch_vccnz .LBB0_545
	v_pk_add_f32 v[62:63], v[62:63], v[234:235]
	v_pk_add_f32 v[60:61], v[60:61], v[232:233]
	v_pk_add_f32 v[58:59], v[58:59], v[238:239]
	v_pk_add_f32 v[56:57], v[56:57], v[236:237]
.LBB0_545:
	v_add_u32_e32 v120, 0x80, v219
	v_lshl_add_u32 v194, v120, 11, v204
	v_lshl_add_u64 v[122:123], v[194:195], 1, s[72:73]
	s_waitcnt vmcnt(12)
	v_pk_add_f32 v[54:55], v[54:55], v[118:119]
	v_pk_add_f32 v[52:53], v[52:53], v[116:117]
	v_pk_add_f32 v[50:51], v[50:51], v[114:115]
	s_and_b64 vcc, exec, s[6:7]
	v_pk_add_f32 v[48:49], v[48:49], v[112:113]
	v_cvt_pk_bf16_f32 v128, v60, v61
	v_cvt_pk_bf16_f32 v129, v62, v63
	v_cvt_pk_bf16_f32 v130, v56, v57
	v_cvt_pk_bf16_f32 v131, v58, v59
	global_store_dwordx4 v[122:123], v[128:131], off
	s_cbranch_vccnz .LBB0_547
	v_pk_add_f32 v[54:55], v[54:55], v[242:243]
	v_pk_add_f32 v[52:53], v[52:53], v[240:241]
	v_pk_add_f32 v[50:51], v[50:51], v[246:247]
	v_pk_add_f32 v[48:49], v[48:49], v[244:245]

.LBB0_549:
	s_or_b64 exec, exec, s[30:31]
	s_waitcnt vmcnt(12)
	v_pk_add_f32 v[46:47], v[46:47], v[110:111]
	v_pk_add_f32 v[44:45], v[44:45], v[108:109]
	v_pk_add_f32 v[42:43], v[42:43], v[106:107]
	s_and_b64 vcc, exec, s[6:7]
	v_pk_add_f32 v[40:41], v[40:41], v[104:105]
	s_cbranch_vccnz .LBB0_551
	s_waitcnt lgkmcnt(0)
	v_pk_add_f32 v[46:47], v[46:47], v[234:235]
	v_pk_add_f32 v[44:45], v[44:45], v[232:233]
	v_pk_add_f32 v[42:43], v[42:43], v[238:239]
	v_pk_add_f32 v[40:41], v[40:41], v[236:237]
.LBB0_551:
	v_add_u32_e32 v48, 0x90, v219
	v_lshl_add_u32 v194, v48, 11, v204
	v_lshl_add_u64 v[54:55], v[194:195], 1, s[72:73]
	s_waitcnt vmcnt(10)
	v_pk_add_f32 v[38:39], v[38:39], v[102:103]
	v_pk_add_f32 v[36:37], v[36:37], v[100:101]
	v_pk_add_f32 v[34:35], v[34:35], v[98:99]
	s_and_b64 vcc, exec, s[6:7]
	v_pk_add_f32 v[32:33], v[32:33], v[96:97]
	v_cvt_pk_bf16_f32 v50, v44, v45
	v_cvt_pk_bf16_f32 v51, v46, v47
	v_cvt_pk_bf16_f32 v52, v40, v41
	s_waitcnt lgkmcnt(0)
	v_cvt_pk_bf16_f32 v53, v42, v43
	global_store_dwordx4 v[54:55], v[50:53], off
	s_cbranch_vccnz .LBB0_553
	v_pk_add_f32 v[38:39], v[38:39], v[242:243]
	v_pk_add_f32 v[36:37], v[36:37], v[240:241]
	v_pk_add_f32 v[34:35], v[34:35], v[246:247]
	v_pk_add_f32 v[32:33], v[32:33], v[244:245]

.LBB0_555:
	s_or_b64 exec, exec, s[30:31]
	s_waitcnt vmcnt(10)
	v_pk_add_f32 v[30:31], v[30:31], v[94:95]
	v_pk_add_f32 v[28:29], v[28:29], v[92:93]
	v_pk_add_f32 v[26:27], v[26:27], v[90:91]
	s_and_b64 vcc, exec, s[6:7]
	v_pk_add_f32 v[24:25], v[24:25], v[88:89]
	s_cbranch_vccnz .LBB0_557
	s_waitcnt lgkmcnt(0)
	v_pk_add_f32 v[30:31], v[30:31], v[234:235]
	v_pk_add_f32 v[28:29], v[28:29], v[232:233]
	v_pk_add_f32 v[26:27], v[26:27], v[238:239]
	v_pk_add_f32 v[24:25], v[24:25], v[236:237]
.LBB0_557:
	v_add_u32_e32 v32, 0xa0, v219
	v_lshl_add_u32 v194, v32, 11, v204
	v_lshl_add_u64 v[38:39], v[194:195], 1, s[72:73]
	s_waitcnt vmcnt(8)
	v_pk_add_f32 v[22:23], v[22:23], v[86:87]
	v_pk_add_f32 v[20:21], v[20:21], v[84:85]
	v_pk_add_f32 v[18:19], v[18:19], v[82:83]
	s_and_b64 vcc, exec, s[6:7]
	v_pk_add_f32 v[16:17], v[16:17], v[80:81]
	v_cvt_pk_bf16_f32 v34, v28, v29
	v_cvt_pk_bf16_f32 v35, v30, v31
	v_cvt_pk_bf16_f32 v36, v24, v25
	s_waitcnt lgkmcnt(0)
	v_cvt_pk_bf16_f32 v37, v26, v27
	global_store_dwordx4 v[38:39], v[34:37], off
	s_cbranch_vccnz .LBB0_559
	v_pk_add_f32 v[22:23], v[22:23], v[242:243]
	v_pk_add_f32 v[20:21], v[20:21], v[240:241]
	v_pk_add_f32 v[18:19], v[18:19], v[246:247]
	v_pk_add_f32 v[16:17], v[16:17], v[244:245]

.LBB0_561:
	s_or_b64 exec, exec, s[30:31]
	s_waitcnt vmcnt(8)
	v_pk_add_f32 v[14:15], v[14:15], v[78:79]
	v_pk_add_f32 v[12:13], v[12:13], v[76:77]
	v_pk_add_f32 v[10:11], v[10:11], v[74:75]
	s_and_b64 vcc, exec, s[6:7]
	v_pk_add_f32 v[8:9], v[8:9], v[72:73]
	s_cbranch_vccnz .LBB0_563
	s_waitcnt lgkmcnt(0)
	v_pk_add_f32 v[14:15], v[14:15], v[234:235]
	v_pk_add_f32 v[12:13], v[12:13], v[232:233]
	v_pk_add_f32 v[10:11], v[10:11], v[238:239]
	v_pk_add_f32 v[8:9], v[8:9], v[236:237]
.LBB0_563:
	v_add_u32_e32 v16, 0xb0, v219
	v_lshl_add_u32 v194, v16, 11, v204
	v_lshl_add_u64 v[22:23], v[194:195], 1, s[72:73]
	s_waitcnt vmcnt(6)
	v_pk_add_f32 v[6:7], v[6:7], v[70:71]
	v_pk_add_f32 v[4:5], v[4:5], v[68:69]
	v_pk_add_f32 v[2:3], v[2:3], v[66:67]
	s_and_b64 vcc, exec, s[6:7]
	v_pk_add_f32 v[0:1], v[0:1], v[64:65]
	v_cvt_pk_bf16_f32 v18, v12, v13
	v_cvt_pk_bf16_f32 v19, v14, v15
	v_cvt_pk_bf16_f32 v20, v8, v9
	s_waitcnt lgkmcnt(0)
	v_cvt_pk_bf16_f32 v21, v10, v11
	global_store_dwordx4 v[22:23], v[18:21], off
	s_cbranch_vccnz .LBB0_565
	v_pk_add_f32 v[6:7], v[6:7], v[242:243]
	v_pk_add_f32 v[4:5], v[4:5], v[240:241]
	v_pk_add_f32 v[2:3], v[2:3], v[246:247]
	v_pk_add_f32 v[0:1], v[0:1], v[244:245]
